# static s_setprio 1 for waves 4-7 from the layer loop on, all 88 per-segment toggles removed
# baseline (speedup 1.0000x reference)
.LBB0_378:
	v_readfirstlane_b32 s100, v244
	s_cmpk_lt_u32 s100, 0x100
	s_cbranch_scc1 .Lsp_lo
	s_setprio 1

.LBB0_389:
	s_add_u32 s24, s22, 0xfffc0080
	s_addc_u32 s25, s23, -1
	s_add_i32 s35, 0, 0x10000
	s_cmp_eq_u32 s34, 12
	s_cselect_b32 s27, s21, s25
	s_cselect_b32 s26, s28, s24
	v_add_u32_e32 v128, s35, v184
	s_cselect_b32 s25, s19, s31
	s_cselect_b32 s24, s29, s30
	s_add_i32 s38, 0, 0x14000
	ds_read_b128 v[130:133], v128
	ds_read_b128 v[134:137], v128 offset:1024
	ds_read_b128 v[138:141], v128 offset:2048
	ds_read_b128 v[142:145], v128 offset:3072
	v_add_u32_e32 v128, s38, v184
	ds_read_b128 v[154:157], v128
	ds_read_b128 v[158:161], v128 offset:1024
	ds_read_b128 v[162:165], v128 offset:2048
	ds_read_b128 v[166:169], v128 offset:3072
	v_lshl_add_u64 v[206:207], s[22:23], 0, v[150:151]
	s_add_i32 m0, s73, 0xc000
	ds_read_b128 v[170:173], v185
	ds_read_b128 v[174:177], v185 offset:1024
	ds_read_b128 v[178:181], v185 offset:2048
	ds_read_b128 v[186:189], v185 offset:3072
	ds_read_b128 v[190:193], v185 offset:4096
	ds_read_b128 v[194:197], v185 offset:5120
	ds_read_b128 v[198:201], v185 offset:6144
	ds_read_b128 v[202:205], v185 offset:7168
	global_load_lds_dwordx4 v[206:207], off
	v_lshl_add_u64 v[206:207], s[22:23], 0, v[152:153]
	s_add_i32 m0, s73, 0xe000
	s_nop 0
	global_load_lds_dwordx4 v[206:207], off
	s_waitcnt vmcnt(8)
	s_waitcnt lgkmcnt(0)
	s_barrier
	s_waitcnt lgkmcnt(0)
	v_mfma_f32_16x16x32_bf16 v[124:127], v[130:133], v[170:173], v[124:127]
	v_mfma_f32_16x16x32_bf16 v[120:123], v[138:141], v[170:173], v[120:123]
	v_mfma_f32_16x16x32_bf16 v[108:111], v[130:133], v[178:181], v[108:111]
	v_mfma_f32_16x16x32_bf16 v[104:107], v[138:141], v[178:181], v[104:107]
	v_mfma_f32_16x16x32_bf16 v[92:95], v[130:133], v[190:193], v[92:95]
	v_mfma_f32_16x16x32_bf16 v[88:91], v[138:141], v[190:193], v[88:91]
	v_mfma_f32_16x16x32_bf16 v[76:79], v[130:133], v[198:201], v[76:79]
	v_mfma_f32_16x16x32_bf16 v[72:75], v[138:141], v[198:201], v[72:75]
	v_mfma_f32_16x16x32_bf16 v[124:127], v[134:137], v[174:177], v[124:127]
	v_mfma_f32_16x16x32_bf16 v[120:123], v[142:145], v[174:177], v[120:123]
	v_mfma_f32_16x16x32_bf16 v[108:111], v[134:137], v[186:189], v[108:111]
	v_mfma_f32_16x16x32_bf16 v[104:107], v[142:145], v[186:189], v[104:107]
	v_mfma_f32_16x16x32_bf16 v[92:95], v[134:137], v[194:197], v[92:95]
	v_mfma_f32_16x16x32_bf16 v[88:91], v[142:145], v[194:197], v[88:91]
	v_mfma_f32_16x16x32_bf16 v[76:79], v[134:137], v[202:205], v[76:79]
	v_mfma_f32_16x16x32_bf16 v[72:75], v[142:145], v[202:205], v[72:75]
	v_mfma_f32_16x16x32_bf16 v[116:119], v[154:157], v[170:173], v[116:119]
	v_mfma_f32_16x16x32_bf16 v[112:115], v[162:165], v[170:173], v[112:115]
	v_mfma_f32_16x16x32_bf16 v[100:103], v[154:157], v[178:181], v[100:103]
	v_mfma_f32_16x16x32_bf16 v[96:99], v[162:165], v[178:181], v[96:99]
	v_mfma_f32_16x16x32_bf16 v[84:87], v[154:157], v[190:193], v[84:87]
	v_mfma_f32_16x16x32_bf16 v[80:83], v[162:165], v[190:193], v[80:83]
	v_mfma_f32_16x16x32_bf16 v[68:71], v[154:157], v[198:201], v[68:71]
	v_mfma_f32_16x16x32_bf16 v[64:67], v[162:165], v[198:201], v[64:67]
	v_mfma_f32_16x16x32_bf16 v[116:119], v[158:161], v[174:177], v[116:119]
	v_mfma_f32_16x16x32_bf16 v[112:115], v[166:169], v[174:177], v[112:115]
	v_mfma_f32_16x16x32_bf16 v[100:103], v[158:161], v[186:189], v[100:103]
	v_mfma_f32_16x16x32_bf16 v[96:99], v[166:169], v[186:189], v[96:99]
	v_mfma_f32_16x16x32_bf16 v[84:87], v[158:161], v[194:197], v[84:87]
	v_mfma_f32_16x16x32_bf16 v[80:83], v[166:169], v[194:197], v[80:83]
	v_mfma_f32_16x16x32_bf16 v[68:71], v[158:161], v[202:205], v[68:71]
	v_mfma_f32_16x16x32_bf16 v[64:67], v[166:169], v[202:205], v[64:67]
	s_barrier
	s_add_i32 s35, s35, s4
	v_lshl_add_u64 v[206:207], s[24:25], 0, v[146:147]
	s_mov_b32 m0, s35
	ds_read_b128 v[170:173], v185 offset:16384
	ds_read_b128 v[174:177], v185 offset:17408
	ds_read_b128 v[178:181], v185 offset:18432
	ds_read_b128 v[186:189], v185 offset:19456
	ds_read_b128 v[190:193], v185 offset:20480
	ds_read_b128 v[194:197], v185 offset:21504
	ds_read_b128 v[198:201], v185 offset:22528
	ds_read_b128 v[202:205], v185 offset:23552
	global_load_lds_dwordx4 v[206:207], off
	s_add_i32 m0, s35, 0x2000
	s_add_u32 s36, s24, 0x40000
	v_lshl_add_u64 v[208:209], s[24:25], 0, v[148:149]
	s_addc_u32 s37, s25, 0
	s_add_i32 s35, s38, s4
	global_load_lds_dwordx4 v[208:209], off
	v_lshl_add_u64 v[210:211], s[36:37], 0, v[146:147]
	s_mov_b32 m0, s35
	v_lshl_add_u64 v[212:213], s[26:27], 0, v[148:149]
	global_load_lds_dwordx4 v[210:211], off
	v_lshl_add_u64 v[210:211], s[36:37], 0, v[148:149]
	s_add_i32 m0, s35, 0x2000
	s_nop 0
	global_load_lds_dwordx4 v[210:211], off
	v_lshl_add_u64 v[210:211], s[26:27], 0, v[146:147]
	s_mov_b32 m0, s73
	s_nop 0
	global_load_lds_dwordx4 v[210:211], off
	s_mov_b32 m0, s93
	s_nop 0
	global_load_lds_dwordx4 v[212:213], off
	s_waitcnt vmcnt(8)
	s_waitcnt lgkmcnt(0)
	s_barrier
	s_waitcnt lgkmcnt(0)
	v_mfma_f32_16x16x32_bf16 v[60:63], v[130:133], v[170:173], v[60:63]
	v_mfma_f32_16x16x32_bf16 v[56:59], v[138:141], v[170:173], v[56:59]
	v_mfma_f32_16x16x32_bf16 v[44:47], v[130:133], v[178:181], v[44:47]
	v_mfma_f32_16x16x32_bf16 v[40:43], v[138:141], v[178:181], v[40:43]
	v_mfma_f32_16x16x32_bf16 v[28:31], v[130:133], v[190:193], v[28:31]
	v_mfma_f32_16x16x32_bf16 v[24:27], v[138:141], v[190:193], v[24:27]
	v_mfma_f32_16x16x32_bf16 v[12:15], v[130:133], v[198:201], v[12:15]
	v_mfma_f32_16x16x32_bf16 v[8:11], v[138:141], v[198:201], v[8:11]
	v_mfma_f32_16x16x32_bf16 v[60:63], v[134:137], v[174:177], v[60:63]
	v_mfma_f32_16x16x32_bf16 v[56:59], v[142:145], v[174:177], v[56:59]
	v_mfma_f32_16x16x32_bf16 v[44:47], v[134:137], v[186:189], v[44:47]
	v_mfma_f32_16x16x32_bf16 v[40:43], v[142:145], v[186:189], v[40:43]
	v_mfma_f32_16x16x32_bf16 v[28:31], v[134:137], v[194:197], v[28:31]
	v_mfma_f32_16x16x32_bf16 v[24:27], v[142:145], v[194:197], v[24:27]
	v_mfma_f32_16x16x32_bf16 v[12:15], v[134:137], v[202:205], v[12:15]
	v_mfma_f32_16x16x32_bf16 v[8:11], v[142:145], v[202:205], v[8:11]
	v_mfma_f32_16x16x32_bf16 v[52:55], v[154:157], v[170:173], v[52:55]
	v_mfma_f32_16x16x32_bf16 v[48:51], v[162:165], v[170:173], v[48:51]
	v_mfma_f32_16x16x32_bf16 v[36:39], v[154:157], v[178:181], v[36:39]
	v_mfma_f32_16x16x32_bf16 v[32:35], v[162:165], v[178:181], v[32:35]
	v_mfma_f32_16x16x32_bf16 v[20:23], v[154:157], v[190:193], v[20:23]
	v_mfma_f32_16x16x32_bf16 v[16:19], v[162:165], v[190:193], v[16:19]
	v_mfma_f32_16x16x32_bf16 v[4:7], v[154:157], v[198:201], v[4:7]
	v_mfma_f32_16x16x32_bf16 v[0:3], v[162:165], v[198:201], v[0:3]
	v_mfma_f32_16x16x32_bf16 v[52:55], v[158:161], v[174:177], v[52:55]
	v_mfma_f32_16x16x32_bf16 v[48:51], v[166:169], v[174:177], v[48:51]
	v_mfma_f32_16x16x32_bf16 v[36:39], v[158:161], v[186:189], v[36:39]
	v_mfma_f32_16x16x32_bf16 v[32:35], v[166:169], v[186:189], v[32:35]
	v_mfma_f32_16x16x32_bf16 v[20:23], v[158:161], v[194:197], v[20:23]
	v_mfma_f32_16x16x32_bf16 v[16:19], v[166:169], v[194:197], v[16:19]
	v_mfma_f32_16x16x32_bf16 v[4:7], v[158:161], v[202:205], v[4:7]
	v_mfma_f32_16x16x32_bf16 v[0:3], v[166:169], v[202:205], v[0:3]
	s_barrier
	s_add_i32 s35, 0, 0x18000
	v_add_u32_e32 v128, s35, v184
	s_add_i32 s36, 0, 0x1c000
	ds_read_b128 v[130:133], v128
	ds_read_b128 v[134:137], v128 offset:1024
	ds_read_b128 v[138:141], v128 offset:2048
	ds_read_b128 v[142:145], v128 offset:3072
	v_add_u32_e32 v128, s36, v184
	ds_read_b128 v[154:157], v128
	ds_read_b128 v[158:161], v128 offset:1024
	ds_read_b128 v[162:165], v128 offset:2048
	ds_read_b128 v[166:169], v128 offset:3072
	s_add_u32 s26, s26, 0x40000
	s_addc_u32 s27, s27, 0
	s_mov_b32 m0, s96
	v_lshl_add_u64 v[214:215], s[26:27], 0, v[146:147]
	ds_read_b128 v[170:173], v185 offset:32768
	ds_read_b128 v[174:177], v185 offset:33792
	ds_read_b128 v[178:181], v185 offset:34816
	ds_read_b128 v[186:189], v185 offset:35840
	ds_read_b128 v[190:193], v185 offset:36864
	ds_read_b128 v[194:197], v185 offset:37888
	ds_read_b128 v[198:201], v185 offset:38912
	ds_read_b128 v[202:205], v185 offset:39936
	global_load_lds_dwordx4 v[214:215], off
	v_lshl_add_u64 v[214:215], s[26:27], 0, v[148:149]
	s_mov_b32 m0, s97
	s_nop 0
	global_load_lds_dwordx4 v[214:215], off
	s_waitcnt vmcnt(8)
	s_waitcnt lgkmcnt(0)
	s_barrier
	s_waitcnt lgkmcnt(0)
	v_mfma_f32_16x16x32_bf16 v[124:127], v[130:133], v[170:173], v[124:127]
	v_mfma_f32_16x16x32_bf16 v[120:123], v[138:141], v[170:173], v[120:123]
	v_mfma_f32_16x16x32_bf16 v[108:111], v[130:133], v[178:181], v[108:111]
	v_mfma_f32_16x16x32_bf16 v[104:107], v[138:141], v[178:181], v[104:107]
	v_mfma_f32_16x16x32_bf16 v[92:95], v[130:133], v[190:193], v[92:95]
	v_mfma_f32_16x16x32_bf16 v[88:91], v[138:141], v[190:193], v[88:91]
	v_mfma_f32_16x16x32_bf16 v[76:79], v[130:133], v[198:201], v[76:79]
	v_mfma_f32_16x16x32_bf16 v[72:75], v[138:141], v[198:201], v[72:75]
	v_mfma_f32_16x16x32_bf16 v[124:127], v[134:137], v[174:177], v[124:127]
	v_mfma_f32_16x16x32_bf16 v[120:123], v[142:145], v[174:177], v[120:123]
	v_mfma_f32_16x16x32_bf16 v[108:111], v[134:137], v[186:189], v[108:111]
	v_mfma_f32_16x16x32_bf16 v[104:107], v[142:145], v[186:189], v[104:107]
	v_mfma_f32_16x16x32_bf16 v[92:95], v[134:137], v[194:197], v[92:95]
	v_mfma_f32_16x16x32_bf16 v[88:91], v[142:145], v[194:197], v[88:91]
	v_mfma_f32_16x16x32_bf16 v[76:79], v[134:137], v[202:205], v[76:79]
	v_mfma_f32_16x16x32_bf16 v[72:75], v[142:145], v[202:205], v[72:75]
	v_mfma_f32_16x16x32_bf16 v[116:119], v[154:157], v[170:173], v[116:119]
	v_mfma_f32_16x16x32_bf16 v[112:115], v[162:165], v[170:173], v[112:115]
	v_mfma_f32_16x16x32_bf16 v[100:103], v[154:157], v[178:181], v[100:103]
	v_mfma_f32_16x16x32_bf16 v[96:99], v[162:165], v[178:181], v[96:99]
	v_mfma_f32_16x16x32_bf16 v[84:87], v[154:157], v[190:193], v[84:87]
	v_mfma_f32_16x16x32_bf16 v[80:83], v[162:165], v[190:193], v[80:83]
	v_mfma_f32_16x16x32_bf16 v[68:71], v[154:157], v[198:201], v[68:71]
	v_mfma_f32_16x16x32_bf16 v[64:67], v[162:165], v[198:201], v[64:67]
	v_mfma_f32_16x16x32_bf16 v[116:119], v[158:161], v[174:177], v[116:119]
	v_mfma_f32_16x16x32_bf16 v[112:115], v[166:169], v[174:177], v[112:115]
	v_mfma_f32_16x16x32_bf16 v[100:103], v[158:161], v[186:189], v[100:103]
	v_mfma_f32_16x16x32_bf16 v[96:99], v[166:169], v[186:189], v[96:99]
	v_mfma_f32_16x16x32_bf16 v[84:87], v[158:161], v[194:197], v[84:87]
	v_mfma_f32_16x16x32_bf16 v[80:83], v[166:169], v[194:197], v[80:83]
	v_mfma_f32_16x16x32_bf16 v[68:71], v[158:161], v[202:205], v[68:71]
	v_mfma_f32_16x16x32_bf16 v[64:67], v[166:169], v[202:205], v[64:67]
	s_barrier
	s_add_i32 s26, s35, s4
	v_lshl_add_u64 v[206:207], v[206:207], 0, s[6:7]
	s_mov_b32 m0, s26
	ds_read_b128 v[170:173], v185 offset:49152
	ds_read_b128 v[174:177], v185 offset:50176
	ds_read_b128 v[178:181], v185 offset:51200
	ds_read_b128 v[186:189], v185 offset:52224
	ds_read_b128 v[190:193], v185 offset:53248
	ds_read_b128 v[194:197], v185 offset:54272
	ds_read_b128 v[198:201], v185 offset:55296
	ds_read_b128 v[202:205], v185 offset:56320
	global_load_lds_dwordx4 v[206:207], off
	s_add_i32 m0, s26, 0x2000
	s_add_u32 s24, s24, 0x40080
	v_lshl_add_u64 v[206:207], v[208:209], 0, s[6:7]
	s_addc_u32 s25, s25, 0
	s_add_i32 s26, s36, s4
	global_load_lds_dwordx4 v[206:207], off
	v_lshl_add_u64 v[206:207], s[24:25], 0, v[146:147]
	s_mov_b32 m0, s26
	s_nop 0
	global_load_lds_dwordx4 v[206:207], off
	v_lshl_add_u64 v[206:207], s[24:25], 0, v[148:149]
	s_add_i32 m0, s26, 0x2000
	s_nop 0
	global_load_lds_dwordx4 v[206:207], off
	v_lshl_add_u64 v[206:207], v[210:211], 0, s[6:7]
	s_mov_b32 m0, s85
	s_nop 0
	global_load_lds_dwordx4 v[206:207], off
	v_lshl_add_u64 v[206:207], v[212:213], 0, s[6:7]
	s_mov_b32 m0, s62
	s_nop 0
	global_load_lds_dwordx4 v[206:207], off
	s_waitcnt vmcnt(8)
	s_waitcnt lgkmcnt(0)
	s_barrier
	s_waitcnt lgkmcnt(0)
	v_mfma_f32_16x16x32_bf16 v[60:63], v[130:133], v[170:173], v[60:63]
	v_mfma_f32_16x16x32_bf16 v[56:59], v[138:141], v[170:173], v[56:59]
	v_mfma_f32_16x16x32_bf16 v[44:47], v[130:133], v[178:181], v[44:47]
	v_mfma_f32_16x16x32_bf16 v[40:43], v[138:141], v[178:181], v[40:43]
	v_mfma_f32_16x16x32_bf16 v[28:31], v[130:133], v[190:193], v[28:31]
	v_mfma_f32_16x16x32_bf16 v[24:27], v[138:141], v[190:193], v[24:27]
	v_mfma_f32_16x16x32_bf16 v[12:15], v[130:133], v[198:201], v[12:15]
	v_mfma_f32_16x16x32_bf16 v[8:11], v[138:141], v[198:201], v[8:11]
	v_mfma_f32_16x16x32_bf16 v[60:63], v[134:137], v[174:177], v[60:63]
	v_mfma_f32_16x16x32_bf16 v[56:59], v[142:145], v[174:177], v[56:59]
	v_mfma_f32_16x16x32_bf16 v[44:47], v[134:137], v[186:189], v[44:47]
	v_mfma_f32_16x16x32_bf16 v[40:43], v[142:145], v[186:189], v[40:43]
	v_mfma_f32_16x16x32_bf16 v[28:31], v[134:137], v[194:197], v[28:31]
	v_mfma_f32_16x16x32_bf16 v[24:27], v[142:145], v[194:197], v[24:27]
	v_mfma_f32_16x16x32_bf16 v[12:15], v[134:137], v[202:205], v[12:15]
	v_mfma_f32_16x16x32_bf16 v[8:11], v[142:145], v[202:205], v[8:11]
	v_mfma_f32_16x16x32_bf16 v[52:55], v[154:157], v[170:173], v[52:55]
	v_mfma_f32_16x16x32_bf16 v[48:51], v[162:165], v[170:173], v[48:51]
	v_mfma_f32_16x16x32_bf16 v[36:39], v[154:157], v[178:181], v[36:39]
	v_mfma_f32_16x16x32_bf16 v[32:35], v[162:165], v[178:181], v[32:35]
	v_mfma_f32_16x16x32_bf16 v[20:23], v[154:157], v[190:193], v[20:23]
	v_mfma_f32_16x16x32_bf16 v[16:19], v[162:165], v[190:193], v[16:19]
	v_mfma_f32_16x16x32_bf16 v[4:7], v[154:157], v[198:201], v[4:7]
	v_mfma_f32_16x16x32_bf16 v[0:3], v[162:165], v[198:201], v[0:3]
	v_mfma_f32_16x16x32_bf16 v[52:55], v[158:161], v[174:177], v[52:55]
	v_mfma_f32_16x16x32_bf16 v[48:51], v[166:169], v[174:177], v[48:51]
	v_mfma_f32_16x16x32_bf16 v[36:39], v[158:161], v[186:189], v[36:39]
	v_mfma_f32_16x16x32_bf16 v[32:35], v[166:169], v[186:189], v[32:35]
	v_mfma_f32_16x16x32_bf16 v[20:23], v[158:161], v[194:197], v[20:23]
	v_mfma_f32_16x16x32_bf16 v[16:19], v[166:169], v[194:197], v[16:19]
	v_mfma_f32_16x16x32_bf16 v[4:7], v[158:161], v[202:205], v[4:7]
	v_mfma_f32_16x16x32_bf16 v[0:3], v[166:169], v[202:205], v[0:3]
	s_barrier
	s_add_i32 s34, s34, 2
	s_add_u32 s22, s22, 0x100
	s_addc_u32 s23, s23, 0
	s_add_u32 s30, s30, 0x100
	s_addc_u32 s31, s31, 0
	s_cmp_gt_u32 s34, 13
	s_cbranch_scc0 .LBB0_389
	s_and_b64 vcc, exec, s[58:59]
	s_cbranch_vccz .LBB0_392
	s_barrier

.LBB0_935:
	v_add_u32_e32 v142, 0x10000, v249
	v_add_u32_e32 v146, 0x14000, v249
	ds_read_b128 v[130:133], v142
	ds_read_b128 v[134:137], v142 offset:1024
	ds_read_b128 v[138:141], v142 offset:2048
	ds_read_b128 v[142:145], v142 offset:3072
	ds_read_b128 v[150:153], v146
	ds_read_b128 v[154:157], v146 offset:1024
	ds_read_b128 v[158:161], v146 offset:2048
	ds_read_b128 v[146:149], v146 offset:3072
	s_waitcnt lgkmcnt(0)
	v_lshl_add_u64 v[194:195], v[240:241], 0, s[18:19]
	s_add_i32 m0, s26, 0xc000
	ds_read_b128 v[186:189], v246
	ds_read_b128 v[190:193], v246 offset:1024
	ds_read_b128 v[178:181], v246 offset:2048
	ds_read_b128 v[182:185], v246 offset:3072
	ds_read_b128 v[170:173], v246 offset:4096
	ds_read_b128 v[174:177], v246 offset:5120
	ds_read_b128 v[162:165], v246 offset:6144
	ds_read_b128 v[166:169], v246 offset:7168
	global_load_lds_dwordx4 v[194:195], off
	v_lshl_add_u64 v[194:195], v[242:243], 0, s[18:19]
	s_add_i32 m0, s26, 0xe000
	s_nop 0
	global_load_lds_dwordx4 v[194:195], off
	s_waitcnt vmcnt(8)
	s_waitcnt lgkmcnt(0)
	s_barrier
	s_mov_b64 s[20:21], -1
	s_and_b64 vcc, exec, s[56:57]
	s_cbranch_vccz .LBB0_937
	s_waitcnt lgkmcnt(0)
	v_mfma_f32_16x16x32_bf16 v[194:197], v[150:153], v[186:189], v[116:119]
	s_mov_b64 s[20:21], 0
	v_mfma_f32_16x16x32_bf16 v[198:201], v[158:161], v[186:189], v[112:115]
	v_mfma_f32_16x16x32_bf16 v[202:205], v[150:153], v[178:181], v[108:111]
	v_mfma_f32_16x16x32_bf16 v[206:209], v[158:161], v[178:181], v[104:107]
	v_mfma_f32_16x16x32_bf16 v[210:213], v[150:153], v[170:173], v[100:103]
	v_mfma_f32_16x16x32_bf16 v[214:217], v[158:161], v[170:173], v[96:99]
	v_mfma_f32_16x16x32_bf16 v[218:221], v[150:153], v[162:165], v[72:75]
	v_mfma_f32_16x16x32_bf16 v[222:225], v[158:161], v[162:165], v[64:67]
	v_mfma_f32_16x16x32_bf16 v[194:197], v[154:157], v[190:193], v[194:197]
	v_mfma_f32_16x16x32_bf16 v[198:201], v[146:149], v[190:193], v[198:201]
	v_mfma_f32_16x16x32_bf16 v[202:205], v[154:157], v[182:185], v[202:205]
	v_mfma_f32_16x16x32_bf16 v[206:209], v[146:149], v[182:185], v[206:209]
	v_mfma_f32_16x16x32_bf16 v[210:213], v[154:157], v[174:177], v[210:213]
	v_mfma_f32_16x16x32_bf16 v[214:217], v[146:149], v[174:177], v[214:217]
	v_mfma_f32_16x16x32_bf16 v[218:221], v[154:157], v[166:169], v[218:221]
	v_mfma_f32_16x16x32_bf16 v[222:225], v[146:149], v[166:169], v[222:225]

.LBB0_940:
	s_add_u32 s20, s44, s18
	s_addc_u32 s21, s45, s19
	s_add_u32 s20, s20, 0x4800100
	s_addc_u32 s21, s21, 0
	s_add_u32 s24, s46, s18
	s_addc_u32 s25, s47, s19
	s_cmpk_eq_i32 s18, 0x700
	s_cselect_b32 s23, s17, s21
	s_cselect_b32 s22, s16, s20
	s_cselect_b32 s21, s15, s25
	s_cselect_b32 s20, s14, s24
	s_barrier
	s_mov_b32 m0, s27
	v_lshl_add_u64 v[226:227], s[20:21], 0, v[128:129]
	s_add_u32 s24, s20, 0x40000
	s_waitcnt lgkmcnt(0)
	ds_read_b128 v[186:189], v246 offset:16384
	ds_read_b128 v[190:193], v246 offset:17408
	ds_read_b128 v[178:181], v246 offset:18432
	ds_read_b128 v[182:185], v246 offset:19456
	ds_read_b128 v[170:173], v246 offset:20480
	ds_read_b128 v[174:177], v246 offset:21504
	ds_read_b128 v[162:165], v246 offset:22528
	ds_read_b128 v[166:169], v246 offset:23552
	global_load_lds_dwordx4 v[226:227], off
	v_lshl_add_u64 v[228:229], s[20:21], 0, v[238:239]
	s_mov_b32 m0, s28
	s_addc_u32 s25, s21, 0
	global_load_lds_dwordx4 v[228:229], off
	v_lshl_add_u64 v[194:195], s[24:25], 0, v[128:129]
	s_mov_b32 m0, s29
	v_lshl_add_u64 v[230:231], s[22:23], 0, v[128:129]
	global_load_lds_dwordx4 v[194:195], off
	v_lshl_add_u64 v[194:195], s[24:25], 0, v[238:239]
	s_mov_b32 m0, s30
	v_lshl_add_u64 v[232:233], s[22:23], 0, v[238:239]
	global_load_lds_dwordx4 v[194:195], off
	s_mov_b32 m0, s26
	s_nop 0
	global_load_lds_dwordx4 v[230:231], off
	s_mov_b32 m0, s31
	s_nop 0
	global_load_lds_dwordx4 v[232:233], off
	s_waitcnt vmcnt(8)
	s_waitcnt lgkmcnt(0)
	s_barrier
	s_mov_b64 s[24:25], -1
	s_and_b64 vcc, exec, s[56:57]
	s_cbranch_vccz .LBB0_942
	s_waitcnt lgkmcnt(0)
	v_mfma_f32_16x16x32_bf16 v[194:197], v[150:153], v[186:189], v[76:79]
	s_mov_b64 s[24:25], 0
	v_mfma_f32_16x16x32_bf16 v[202:205], v[150:153], v[178:181], v[44:47]
	v_mfma_f32_16x16x32_bf16 v[210:213], v[150:153], v[170:173], v[36:39]
	v_mfma_f32_16x16x32_bf16 v[150:153], v[150:153], v[162:165], v[12:15]
	v_mfma_f32_16x16x32_bf16 v[198:201], v[158:161], v[186:189], v[68:71]
	v_mfma_f32_16x16x32_bf16 v[206:209], v[158:161], v[178:181], v[40:43]
	v_mfma_f32_16x16x32_bf16 v[214:217], v[158:161], v[170:173], v[32:35]
	v_mfma_f32_16x16x32_bf16 v[218:221], v[154:157], v[166:169], v[150:153]
	v_mfma_f32_16x16x32_bf16 v[150:153], v[158:161], v[162:165], v[8:11]
	v_mfma_f32_16x16x32_bf16 v[194:197], v[154:157], v[190:193], v[194:197]
	v_mfma_f32_16x16x32_bf16 v[198:201], v[146:149], v[190:193], v[198:201]
	v_mfma_f32_16x16x32_bf16 v[202:205], v[154:157], v[182:185], v[202:205]
	v_mfma_f32_16x16x32_bf16 v[206:209], v[146:149], v[182:185], v[206:209]
	v_mfma_f32_16x16x32_bf16 v[210:213], v[154:157], v[174:177], v[210:213]
	v_mfma_f32_16x16x32_bf16 v[214:217], v[146:149], v[174:177], v[214:217]
	v_mfma_f32_16x16x32_bf16 v[222:225], v[146:149], v[166:169], v[150:153]

.LBB0_945:
	s_barrier
	v_add_u32_e32 v130, 0x18000, v249
	ds_read_b128 v[138:141], v130
	ds_read_b128 v[142:145], v130 offset:1024
	ds_read_b128 v[146:149], v130 offset:2048
	ds_read_b128 v[150:153], v130 offset:3072
	v_add_u32_e32 v130, 0x1c000, v249
	ds_read_b128 v[158:161], v130
	s_waitcnt lgkmcnt(0)
	ds_read_b128 v[162:165], v130 offset:1024
	ds_read_b128 v[166:169], v130 offset:2048
	ds_read_b128 v[154:157], v130 offset:3072
	s_add_u32 s22, s22, 0x40000
	s_addc_u32 s23, s23, 0
	s_mov_b32 m0, s34
	v_lshl_add_u64 v[130:131], s[22:23], 0, v[128:129]
	ds_read_b128 v[194:197], v246 offset:32768
	ds_read_b128 v[198:201], v246 offset:33792
	ds_read_b128 v[186:189], v246 offset:34816
	ds_read_b128 v[190:193], v246 offset:35840
	ds_read_b128 v[178:181], v246 offset:36864
	ds_read_b128 v[182:185], v246 offset:37888
	ds_read_b128 v[174:177], v246 offset:38912
	ds_read_b128 v[170:173], v246 offset:39936
	global_load_lds_dwordx4 v[130:131], off
	v_lshl_add_u64 v[130:131], s[22:23], 0, v[238:239]
	s_mov_b32 m0, s35
	s_nop 0
	global_load_lds_dwordx4 v[130:131], off
	s_waitcnt vmcnt(8)
	s_waitcnt lgkmcnt(0)
	s_barrier
	s_mov_b64 s[22:23], -1
	s_and_b64 vcc, exec, s[56:57]
	s_cbranch_vccz .LBB0_947
	s_waitcnt lgkmcnt(0)
	v_mfma_f32_16x16x32_bf16 v[130:133], v[158:161], v[194:197], v[116:119]
	s_mov_b64 s[22:23], 0
	v_mfma_f32_16x16x32_bf16 v[134:137], v[162:165], v[198:201], v[130:133]
	v_mfma_f32_16x16x32_bf16 v[130:133], v[166:169], v[194:197], v[112:115]
	v_mfma_f32_16x16x32_bf16 v[202:205], v[158:161], v[186:189], v[108:111]
	v_mfma_f32_16x16x32_bf16 v[206:209], v[166:169], v[186:189], v[104:107]
	v_mfma_f32_16x16x32_bf16 v[210:213], v[158:161], v[178:181], v[100:103]
	v_mfma_f32_16x16x32_bf16 v[214:217], v[166:169], v[178:181], v[96:99]
	v_mfma_f32_16x16x32_bf16 v[218:221], v[158:161], v[174:177], v[72:75]
	v_mfma_f32_16x16x32_bf16 v[222:225], v[166:169], v[174:177], v[64:67]
	v_mfma_f32_16x16x32_bf16 v[130:133], v[154:157], v[198:201], v[130:133]
	v_mfma_f32_16x16x32_bf16 v[202:205], v[162:165], v[190:193], v[202:205]
	v_mfma_f32_16x16x32_bf16 v[206:209], v[154:157], v[190:193], v[206:209]
	v_mfma_f32_16x16x32_bf16 v[210:213], v[162:165], v[182:185], v[210:213]
	v_mfma_f32_16x16x32_bf16 v[214:217], v[154:157], v[182:185], v[214:217]
	v_mfma_f32_16x16x32_bf16 v[218:221], v[162:165], v[170:173], v[218:221]
	v_mfma_f32_16x16x32_bf16 v[222:225], v[154:157], v[170:173], v[222:225]

.LBB0_950:
	s_barrier
	s_mov_b32 m0, s37
	v_lshl_add_u64 v[202:203], v[226:227], 0, s[6:7]
	s_add_u32 s20, s20, 0x40080
	s_waitcnt lgkmcnt(0)
	ds_read_b128 v[194:197], v246 offset:49152
	ds_read_b128 v[198:201], v246 offset:50176
	ds_read_b128 v[186:189], v246 offset:51200
	ds_read_b128 v[190:193], v246 offset:52224
	ds_read_b128 v[178:181], v246 offset:53248
	ds_read_b128 v[182:185], v246 offset:54272
	ds_read_b128 v[170:173], v246 offset:55296
	ds_read_b128 v[174:177], v246 offset:56320
	global_load_lds_dwordx4 v[202:203], off
	v_lshl_add_u64 v[202:203], v[228:229], 0, s[6:7]
	s_mov_b32 m0, s38
	s_addc_u32 s21, s21, 0
	global_load_lds_dwordx4 v[202:203], off
	v_lshl_add_u64 v[202:203], s[20:21], 0, v[128:129]
	s_mov_b32 m0, s5
	s_nop 0
	global_load_lds_dwordx4 v[202:203], off
	v_lshl_add_u64 v[202:203], s[20:21], 0, v[238:239]
	s_mov_b32 m0, s41
	s_nop 0
	global_load_lds_dwordx4 v[202:203], off
	v_lshl_add_u64 v[202:203], v[230:231], 0, s[6:7]
	s_mov_b32 m0, s39
	s_nop 0
	global_load_lds_dwordx4 v[202:203], off
	v_lshl_add_u64 v[202:203], v[232:233], 0, s[6:7]
	s_mov_b32 m0, s40
	s_nop 0
	global_load_lds_dwordx4 v[202:203], off
	s_waitcnt vmcnt(8)
	s_waitcnt lgkmcnt(0)
	s_barrier
	s_mov_b64 s[20:21], -1
	s_and_b64 vcc, exec, s[56:57]
	s_cbranch_vccz .LBB0_952
	s_waitcnt lgkmcnt(0)
	v_mfma_f32_16x16x32_bf16 v[202:205], v[158:161], v[194:197], v[76:79]
	s_mov_b64 s[20:21], 0
	v_mfma_f32_16x16x32_bf16 v[210:213], v[158:161], v[186:189], v[44:47]
	v_mfma_f32_16x16x32_bf16 v[218:221], v[158:161], v[178:181], v[36:39]
	v_mfma_f32_16x16x32_bf16 v[158:161], v[158:161], v[170:173], v[12:15]
	v_mfma_f32_16x16x32_bf16 v[206:209], v[166:169], v[194:197], v[68:71]
	v_mfma_f32_16x16x32_bf16 v[214:217], v[166:169], v[186:189], v[40:43]
	v_mfma_f32_16x16x32_bf16 v[222:225], v[166:169], v[178:181], v[32:35]
	v_mfma_f32_16x16x32_bf16 v[226:229], v[162:165], v[174:177], v[158:161]
	v_mfma_f32_16x16x32_bf16 v[158:161], v[166:169], v[170:173], v[8:11]
	v_mfma_f32_16x16x32_bf16 v[202:205], v[162:165], v[198:201], v[202:205]
	v_mfma_f32_16x16x32_bf16 v[206:209], v[154:157], v[198:201], v[206:209]
	v_mfma_f32_16x16x32_bf16 v[210:213], v[162:165], v[190:193], v[210:213]
	v_mfma_f32_16x16x32_bf16 v[214:217], v[154:157], v[190:193], v[214:217]
	v_mfma_f32_16x16x32_bf16 v[218:221], v[162:165], v[182:185], v[218:221]
	v_mfma_f32_16x16x32_bf16 v[222:225], v[154:157], v[182:185], v[222:225]
	v_mfma_f32_16x16x32_bf16 v[230:233], v[154:157], v[174:177], v[158:161]

.Lpc1_skb_1:
	v_lshl_add_u64 v[206:207], s[30:31], 0, v[202:203]
	s_add_i32 m0, s39, 0xc000
	ds_read_b128 v[186:189], v217
	ds_read_b128 v[190:193], v217 offset:1024
	ds_read_b128 v[178:181], v217 offset:2048
	ds_read_b128 v[182:185], v217 offset:3072
	ds_read_b128 v[170:173], v217 offset:4096
	ds_read_b128 v[174:177], v217 offset:5120
	ds_read_b128 v[162:165], v217 offset:6144
	ds_read_b128 v[166:169], v217 offset:7168
	global_load_lds_dwordx4 v[206:207], off
	v_lshl_add_u64 v[206:207], s[30:31], 0, v[204:205]
	s_add_i32 m0, s39, 0xe000
	v_cndmask_b32_e64 v128, 0, 1, s[52:53]
	global_load_lds_dwordx4 v[206:207], off
	s_waitcnt vmcnt(6)
	s_waitcnt lgkmcnt(0)
	v_cmp_ne_u32_e64 s[44:45], 1, v128
	s_andn2_b64 vcc, exec, s[52:53]
	s_barrier
	s_cbranch_vccnz .LBB0_1283
	s_waitcnt lgkmcnt(0)
	v_mfma_f32_16x16x32_bf16 v[124:127], v[146:149], v[186:189], v[124:127]
	v_mfma_f32_16x16x32_bf16 v[120:123], v[154:157], v[186:189], v[120:123]
	v_mfma_f32_16x16x32_bf16 v[108:111], v[146:149], v[178:181], v[108:111]
	v_mfma_f32_16x16x32_bf16 v[104:107], v[154:157], v[178:181], v[104:107]
	v_mfma_f32_16x16x32_bf16 v[92:95], v[146:149], v[170:173], v[92:95]
	v_mfma_f32_16x16x32_bf16 v[88:91], v[154:157], v[170:173], v[88:91]
	v_mfma_f32_16x16x32_bf16 v[76:79], v[146:149], v[162:165], v[76:79]
	v_mfma_f32_16x16x32_bf16 v[72:75], v[154:157], v[162:165], v[72:75]
	v_mfma_f32_16x16x32_bf16 v[124:127], v[150:153], v[190:193], v[124:127]
	v_mfma_f32_16x16x32_bf16 v[120:123], v[158:161], v[190:193], v[120:123]
	v_mfma_f32_16x16x32_bf16 v[108:111], v[150:153], v[182:185], v[108:111]
	v_mfma_f32_16x16x32_bf16 v[104:107], v[158:161], v[182:185], v[104:107]
	v_mfma_f32_16x16x32_bf16 v[92:95], v[150:153], v[174:177], v[92:95]
	v_mfma_f32_16x16x32_bf16 v[88:91], v[158:161], v[174:177], v[88:91]
	v_mfma_f32_16x16x32_bf16 v[76:79], v[150:153], v[166:169], v[76:79]
	v_mfma_f32_16x16x32_bf16 v[72:75], v[158:161], v[166:169], v[72:75]
.LBB0_1283:
	v_cndmask_b32_e64 v128, 0, 1, s[94:95]
	v_cmp_ne_u32_e64 s[46:47], 1, v128
	s_andn2_b64 vcc, exec, s[94:95]
	s_cbranch_vccnz .LBB0_1285
	s_waitcnt lgkmcnt(0)
	v_mfma_f32_16x16x32_bf16 v[116:119], v[130:133], v[186:189], v[116:119]
	v_mfma_f32_16x16x32_bf16 v[112:115], v[138:141], v[186:189], v[112:115]
	v_mfma_f32_16x16x32_bf16 v[100:103], v[130:133], v[178:181], v[100:103]
	v_mfma_f32_16x16x32_bf16 v[96:99], v[138:141], v[178:181], v[96:99]
	v_mfma_f32_16x16x32_bf16 v[84:87], v[130:133], v[170:173], v[84:87]
	v_mfma_f32_16x16x32_bf16 v[80:83], v[138:141], v[170:173], v[80:83]
	v_mfma_f32_16x16x32_bf16 v[68:71], v[130:133], v[162:165], v[68:71]
	v_mfma_f32_16x16x32_bf16 v[64:67], v[138:141], v[162:165], v[64:67]
	v_mfma_f32_16x16x32_bf16 v[116:119], v[134:137], v[190:193], v[116:119]
	v_mfma_f32_16x16x32_bf16 v[112:115], v[142:145], v[190:193], v[112:115]
	v_mfma_f32_16x16x32_bf16 v[100:103], v[134:137], v[182:185], v[100:103]
	v_mfma_f32_16x16x32_bf16 v[96:99], v[142:145], v[182:185], v[96:99]
	v_mfma_f32_16x16x32_bf16 v[84:87], v[134:137], v[174:177], v[84:87]
	v_mfma_f32_16x16x32_bf16 v[80:83], v[142:145], v[174:177], v[80:83]
	v_mfma_f32_16x16x32_bf16 v[68:71], v[134:137], v[166:169], v[68:71]
	v_mfma_f32_16x16x32_bf16 v[64:67], v[142:145], v[166:169], v[64:67]

.Lpc1_dsk_3:
	s_and_b64 vcc, exec, s[44:45]
	v_lshl_add_u64 v[210:211], s[36:37], 0, v[200:201]
	s_mov_b32 m0, s39
	s_nop 0
	global_load_lds_dwordx4 v[210:211], off
	s_mov_b32 m0, s60
	s_nop 0
	global_load_lds_dwordx4 v[212:213], off
	s_waitcnt vmcnt(6)
	s_waitcnt lgkmcnt(0)
	s_barrier
	s_cbranch_vccnz .LBB0_1287
	s_waitcnt lgkmcnt(0)
	v_mfma_f32_16x16x32_bf16 v[60:63], v[146:149], v[186:189], v[60:63]
	v_mfma_f32_16x16x32_bf16 v[56:59], v[154:157], v[186:189], v[56:59]
	v_mfma_f32_16x16x32_bf16 v[44:47], v[146:149], v[178:181], v[44:47]
	v_mfma_f32_16x16x32_bf16 v[40:43], v[154:157], v[178:181], v[40:43]
	v_mfma_f32_16x16x32_bf16 v[28:31], v[146:149], v[170:173], v[28:31]
	v_mfma_f32_16x16x32_bf16 v[24:27], v[154:157], v[170:173], v[24:27]
	v_mfma_f32_16x16x32_bf16 v[12:15], v[146:149], v[162:165], v[12:15]
	v_mfma_f32_16x16x32_bf16 v[8:11], v[154:157], v[162:165], v[8:11]
	v_mfma_f32_16x16x32_bf16 v[60:63], v[150:153], v[190:193], v[60:63]
	v_mfma_f32_16x16x32_bf16 v[56:59], v[158:161], v[190:193], v[56:59]
	v_mfma_f32_16x16x32_bf16 v[44:47], v[150:153], v[182:185], v[44:47]
	v_mfma_f32_16x16x32_bf16 v[40:43], v[158:161], v[182:185], v[40:43]
	v_mfma_f32_16x16x32_bf16 v[28:31], v[150:153], v[174:177], v[28:31]
	v_mfma_f32_16x16x32_bf16 v[24:27], v[158:161], v[174:177], v[24:27]
	v_mfma_f32_16x16x32_bf16 v[12:15], v[150:153], v[166:169], v[12:15]
	v_mfma_f32_16x16x32_bf16 v[8:11], v[158:161], v[166:169], v[8:11]
.LBB0_1287:
	s_and_b64 vcc, exec, s[46:47]
	s_cbranch_vccnz .LBB0_1289
	s_waitcnt lgkmcnt(0)
	v_mfma_f32_16x16x32_bf16 v[52:55], v[130:133], v[186:189], v[52:55]
	v_mfma_f32_16x16x32_bf16 v[48:51], v[138:141], v[186:189], v[48:51]
	v_mfma_f32_16x16x32_bf16 v[36:39], v[130:133], v[178:181], v[36:39]
	v_mfma_f32_16x16x32_bf16 v[32:35], v[138:141], v[178:181], v[32:35]
	v_mfma_f32_16x16x32_bf16 v[20:23], v[130:133], v[170:173], v[20:23]
	v_mfma_f32_16x16x32_bf16 v[16:19], v[138:141], v[170:173], v[16:19]
	v_mfma_f32_16x16x32_bf16 v[4:7], v[130:133], v[162:165], v[4:7]
	v_mfma_f32_16x16x32_bf16 v[0:3], v[138:141], v[162:165], v[0:3]
	v_mfma_f32_16x16x32_bf16 v[52:55], v[134:137], v[190:193], v[52:55]
	v_mfma_f32_16x16x32_bf16 v[48:51], v[142:145], v[190:193], v[48:51]
	v_mfma_f32_16x16x32_bf16 v[36:39], v[134:137], v[182:185], v[36:39]
	v_mfma_f32_16x16x32_bf16 v[32:35], v[142:145], v[182:185], v[32:35]
	v_mfma_f32_16x16x32_bf16 v[20:23], v[134:137], v[174:177], v[20:23]
	v_mfma_f32_16x16x32_bf16 v[16:19], v[142:145], v[174:177], v[16:19]
	v_mfma_f32_16x16x32_bf16 v[4:7], v[134:137], v[166:169], v[4:7]
	v_mfma_f32_16x16x32_bf16 v[0:3], v[142:145], v[166:169], v[0:3]

.Lpc1_skb_3:
	s_add_u32 s36, s36, 0x20000
	s_addc_u32 s37, s37, 0
	s_mov_b32 m0, s61
	v_lshl_add_u64 v[218:219], s[36:37], 0, v[200:201]
	ds_read_b128 v[186:189], v217 offset:32768
	ds_read_b128 v[190:193], v217 offset:33792
	ds_read_b128 v[178:181], v217 offset:34816
	ds_read_b128 v[182:185], v217 offset:35840
	ds_read_b128 v[170:173], v217 offset:36864
	ds_read_b128 v[174:177], v217 offset:37888
	ds_read_b128 v[162:165], v217 offset:38912
	ds_read_b128 v[166:169], v217 offset:39936
	global_load_lds_dwordx4 v[218:219], off
	v_lshl_add_u64 v[218:219], s[36:37], 0, v[196:197]
	s_mov_b32 m0, s62
	s_and_b64 vcc, exec, s[44:45]
	global_load_lds_dwordx4 v[218:219], off
	s_waitcnt vmcnt(6)
	s_waitcnt lgkmcnt(0)
	s_barrier
	s_cbranch_vccnz .LBB0_1291
	s_waitcnt lgkmcnt(0)
	v_mfma_f32_16x16x32_bf16 v[124:127], v[146:149], v[186:189], v[124:127]
	v_mfma_f32_16x16x32_bf16 v[120:123], v[154:157], v[186:189], v[120:123]
	v_mfma_f32_16x16x32_bf16 v[108:111], v[146:149], v[178:181], v[108:111]
	v_mfma_f32_16x16x32_bf16 v[104:107], v[154:157], v[178:181], v[104:107]
	v_mfma_f32_16x16x32_bf16 v[92:95], v[146:149], v[170:173], v[92:95]
	v_mfma_f32_16x16x32_bf16 v[88:91], v[154:157], v[170:173], v[88:91]
	v_mfma_f32_16x16x32_bf16 v[76:79], v[146:149], v[162:165], v[76:79]
	v_mfma_f32_16x16x32_bf16 v[72:75], v[154:157], v[162:165], v[72:75]
	v_mfma_f32_16x16x32_bf16 v[124:127], v[150:153], v[190:193], v[124:127]
	v_mfma_f32_16x16x32_bf16 v[120:123], v[158:161], v[190:193], v[120:123]
	v_mfma_f32_16x16x32_bf16 v[108:111], v[150:153], v[182:185], v[108:111]
	v_mfma_f32_16x16x32_bf16 v[104:107], v[158:161], v[182:185], v[104:107]
	v_mfma_f32_16x16x32_bf16 v[92:95], v[150:153], v[174:177], v[92:95]
	v_mfma_f32_16x16x32_bf16 v[88:91], v[158:161], v[174:177], v[88:91]
	v_mfma_f32_16x16x32_bf16 v[76:79], v[150:153], v[166:169], v[76:79]
	v_mfma_f32_16x16x32_bf16 v[72:75], v[158:161], v[166:169], v[72:75]
.LBB0_1291:
	s_and_b64 vcc, exec, s[46:47]
	s_cbranch_vccnz .LBB0_1293
	s_waitcnt lgkmcnt(0)
	v_mfma_f32_16x16x32_bf16 v[116:119], v[130:133], v[186:189], v[116:119]
	v_mfma_f32_16x16x32_bf16 v[112:115], v[138:141], v[186:189], v[112:115]
	v_mfma_f32_16x16x32_bf16 v[100:103], v[130:133], v[178:181], v[100:103]
	v_mfma_f32_16x16x32_bf16 v[96:99], v[138:141], v[178:181], v[96:99]
	v_mfma_f32_16x16x32_bf16 v[84:87], v[130:133], v[170:173], v[84:87]
	v_mfma_f32_16x16x32_bf16 v[80:83], v[138:141], v[170:173], v[80:83]
	v_mfma_f32_16x16x32_bf16 v[68:71], v[130:133], v[162:165], v[68:71]
	v_mfma_f32_16x16x32_bf16 v[64:67], v[138:141], v[162:165], v[64:67]
	v_mfma_f32_16x16x32_bf16 v[116:119], v[134:137], v[190:193], v[116:119]
	v_mfma_f32_16x16x32_bf16 v[112:115], v[142:145], v[190:193], v[112:115]
	v_mfma_f32_16x16x32_bf16 v[100:103], v[134:137], v[182:185], v[100:103]
	v_mfma_f32_16x16x32_bf16 v[96:99], v[142:145], v[182:185], v[96:99]
	v_mfma_f32_16x16x32_bf16 v[84:87], v[134:137], v[174:177], v[84:87]
	v_mfma_f32_16x16x32_bf16 v[80:83], v[142:145], v[174:177], v[80:83]
	v_mfma_f32_16x16x32_bf16 v[68:71], v[134:137], v[166:169], v[68:71]
	v_mfma_f32_16x16x32_bf16 v[64:67], v[142:145], v[166:169], v[64:67]

.Lpc1_dsk_7:
	s_and_b64 vcc, exec, s[44:45]
	v_lshl_add_u64 v[206:207], v[210:211], 0, s[6:7]
	s_mov_b32 m0, s68
	s_nop 0
	global_load_lds_dwordx4 v[206:207], off
	v_lshl_add_u64 v[206:207], v[212:213], 0, s[6:7]
	s_mov_b32 m0, s70
	s_nop 0
	global_load_lds_dwordx4 v[206:207], off
	s_waitcnt vmcnt(6)
	s_waitcnt lgkmcnt(0)
	s_barrier
	s_cbranch_vccnz .LBB0_1295
	s_waitcnt lgkmcnt(0)
	v_mfma_f32_16x16x32_bf16 v[60:63], v[146:149], v[186:189], v[60:63]
	v_mfma_f32_16x16x32_bf16 v[56:59], v[154:157], v[186:189], v[56:59]
	v_mfma_f32_16x16x32_bf16 v[44:47], v[146:149], v[178:181], v[44:47]
	v_mfma_f32_16x16x32_bf16 v[40:43], v[154:157], v[178:181], v[40:43]
	v_mfma_f32_16x16x32_bf16 v[28:31], v[146:149], v[170:173], v[28:31]
	v_mfma_f32_16x16x32_bf16 v[24:27], v[154:157], v[170:173], v[24:27]
	v_mfma_f32_16x16x32_bf16 v[12:15], v[146:149], v[162:165], v[12:15]
	v_mfma_f32_16x16x32_bf16 v[8:11], v[154:157], v[162:165], v[8:11]
	v_mfma_f32_16x16x32_bf16 v[60:63], v[150:153], v[190:193], v[60:63]
	v_mfma_f32_16x16x32_bf16 v[56:59], v[158:161], v[190:193], v[56:59]
	v_mfma_f32_16x16x32_bf16 v[44:47], v[150:153], v[182:185], v[44:47]
	v_mfma_f32_16x16x32_bf16 v[40:43], v[158:161], v[182:185], v[40:43]
	v_mfma_f32_16x16x32_bf16 v[28:31], v[150:153], v[174:177], v[28:31]
	v_mfma_f32_16x16x32_bf16 v[24:27], v[158:161], v[174:177], v[24:27]
	v_mfma_f32_16x16x32_bf16 v[12:15], v[150:153], v[166:169], v[12:15]
	v_mfma_f32_16x16x32_bf16 v[8:11], v[158:161], v[166:169], v[8:11]
.LBB0_1295:
	s_and_b64 vcc, exec, s[46:47]
	s_cbranch_vccnz .LBB0_1280
	s_waitcnt lgkmcnt(0)
	v_mfma_f32_16x16x32_bf16 v[52:55], v[130:133], v[186:189], v[52:55]
	v_mfma_f32_16x16x32_bf16 v[48:51], v[138:141], v[186:189], v[48:51]
	v_mfma_f32_16x16x32_bf16 v[36:39], v[130:133], v[178:181], v[36:39]
	v_mfma_f32_16x16x32_bf16 v[32:35], v[138:141], v[178:181], v[32:35]
	v_mfma_f32_16x16x32_bf16 v[20:23], v[130:133], v[170:173], v[20:23]
	v_mfma_f32_16x16x32_bf16 v[16:19], v[138:141], v[170:173], v[16:19]
	v_mfma_f32_16x16x32_bf16 v[4:7], v[130:133], v[162:165], v[4:7]
	v_mfma_f32_16x16x32_bf16 v[0:3], v[138:141], v[162:165], v[0:3]
	v_mfma_f32_16x16x32_bf16 v[52:55], v[134:137], v[190:193], v[52:55]
	v_mfma_f32_16x16x32_bf16 v[48:51], v[142:145], v[190:193], v[48:51]
	v_mfma_f32_16x16x32_bf16 v[36:39], v[134:137], v[182:185], v[36:39]
	v_mfma_f32_16x16x32_bf16 v[32:35], v[142:145], v[182:185], v[32:35]
	v_mfma_f32_16x16x32_bf16 v[20:23], v[134:137], v[174:177], v[20:23]
	v_mfma_f32_16x16x32_bf16 v[16:19], v[142:145], v[174:177], v[16:19]
	v_mfma_f32_16x16x32_bf16 v[4:7], v[134:137], v[166:169], v[4:7]
	v_mfma_f32_16x16x32_bf16 v[0:3], v[142:145], v[166:169], v[0:3]
	s_branch .LBB0_1280

.LBB0_1501:
	s_add_i32 s75, s36, 2
	s_add_u32 s34, s30, 0x100
	s_addc_u32 s35, s31, 0
	s_add_i32 s76, 0, 0x10000
	s_cmp_eq_u32 s1, s36
	s_cselect_b32 s41, s25, s35
	s_cselect_b32 s40, s71, s34
	s_cselect_b32 s37, s23, s74
	s_cselect_b32 s36, s72, s73
	s_add_i32 s77, 0, 0x14000
	v_add_u32_e32 v152, s76, v138
	v_add_u32_e32 v168, s77, v138
	ds_read_b128 v[140:143], v152
	ds_read_b128 v[144:147], v152 offset:1024
	ds_read_b128 v[148:151], v152 offset:2048
	ds_read_b128 v[152:155], v152 offset:3072
	ds_read_b128 v[156:159], v168
	ds_read_b128 v[160:163], v168 offset:1024
	ds_read_b128 v[164:167], v168 offset:2048
	ds_read_b128 v[168:171], v168 offset:3072
	v_lshl_add_u64 v[204:205], s[30:31], 0, v[132:133]
	s_add_i32 m0, s58, 0xc000
	ds_read_b128 v[172:175], v139
	ds_read_b128 v[176:179], v139 offset:1024
	ds_read_b128 v[180:183], v139 offset:2048
	ds_read_b128 v[184:187], v139 offset:3072
	ds_read_b128 v[188:191], v139 offset:4096
	ds_read_b128 v[192:195], v139 offset:5120
	ds_read_b128 v[196:199], v139 offset:6144
	ds_read_b128 v[200:203], v139 offset:7168
	global_load_lds_dwordx4 v[204:205], off
	v_lshl_add_u64 v[204:205], s[30:31], 0, v[134:135]
	s_add_i32 m0, s58, 0xe000
	s_nop 0
	global_load_lds_dwordx4 v[204:205], off
	s_waitcnt vmcnt(8)
	s_waitcnt lgkmcnt(0)
	s_barrier
	s_waitcnt lgkmcnt(0)
	v_mfma_f32_16x16x32_bf16 v[124:127], v[140:143], v[172:175], v[124:127]
	v_mfma_f32_16x16x32_bf16 v[108:111], v[148:151], v[172:175], v[108:111]
	v_mfma_f32_16x16x32_bf16 v[120:123], v[140:143], v[180:183], v[120:123]
	v_mfma_f32_16x16x32_bf16 v[104:107], v[148:151], v[180:183], v[104:107]
	v_mfma_f32_16x16x32_bf16 v[116:119], v[140:143], v[188:191], v[116:119]
	v_mfma_f32_16x16x32_bf16 v[100:103], v[148:151], v[188:191], v[100:103]
	v_mfma_f32_16x16x32_bf16 v[112:115], v[140:143], v[196:199], v[112:115]
	v_mfma_f32_16x16x32_bf16 v[96:99], v[148:151], v[196:199], v[96:99]
	v_mfma_f32_16x16x32_bf16 v[124:127], v[144:147], v[176:179], v[124:127]
	v_mfma_f32_16x16x32_bf16 v[108:111], v[152:155], v[176:179], v[108:111]
	v_mfma_f32_16x16x32_bf16 v[120:123], v[144:147], v[184:187], v[120:123]
	v_mfma_f32_16x16x32_bf16 v[104:107], v[152:155], v[184:187], v[104:107]
	v_mfma_f32_16x16x32_bf16 v[116:119], v[144:147], v[192:195], v[116:119]
	v_mfma_f32_16x16x32_bf16 v[100:103], v[152:155], v[192:195], v[100:103]
	v_mfma_f32_16x16x32_bf16 v[112:115], v[144:147], v[200:203], v[112:115]
	v_mfma_f32_16x16x32_bf16 v[96:99], v[152:155], v[200:203], v[96:99]
	v_mfma_f32_16x16x32_bf16 v[92:95], v[156:159], v[172:175], v[92:95]
	v_mfma_f32_16x16x32_bf16 v[76:79], v[164:167], v[172:175], v[76:79]
	v_mfma_f32_16x16x32_bf16 v[88:91], v[156:159], v[180:183], v[88:91]
	v_mfma_f32_16x16x32_bf16 v[72:75], v[164:167], v[180:183], v[72:75]
	v_mfma_f32_16x16x32_bf16 v[84:87], v[156:159], v[188:191], v[84:87]
	v_mfma_f32_16x16x32_bf16 v[68:71], v[164:167], v[188:191], v[68:71]
	v_mfma_f32_16x16x32_bf16 v[80:83], v[156:159], v[196:199], v[80:83]
	v_mfma_f32_16x16x32_bf16 v[64:67], v[164:167], v[196:199], v[64:67]
	v_mfma_f32_16x16x32_bf16 v[92:95], v[160:163], v[176:179], v[92:95]
	v_mfma_f32_16x16x32_bf16 v[76:79], v[168:171], v[176:179], v[76:79]
	v_mfma_f32_16x16x32_bf16 v[88:91], v[160:163], v[184:187], v[88:91]
	v_mfma_f32_16x16x32_bf16 v[72:75], v[168:171], v[184:187], v[72:75]
	v_mfma_f32_16x16x32_bf16 v[84:87], v[160:163], v[192:195], v[84:87]
	v_mfma_f32_16x16x32_bf16 v[68:71], v[168:171], v[192:195], v[68:71]
	v_mfma_f32_16x16x32_bf16 v[80:83], v[160:163], v[200:203], v[80:83]
	v_mfma_f32_16x16x32_bf16 v[64:67], v[168:171], v[200:203], v[64:67]
	s_barrier
	s_add_i32 s30, s76, s56
	v_lshl_add_u64 v[204:205], s[36:37], 0, v[128:129]
	s_mov_b32 m0, s30
	ds_read_b128 v[172:175], v139 offset:16384
	ds_read_b128 v[176:179], v139 offset:17408
	ds_read_b128 v[180:183], v139 offset:18432
	ds_read_b128 v[184:187], v139 offset:19456
	ds_read_b128 v[188:191], v139 offset:20480
	ds_read_b128 v[192:195], v139 offset:21504
	ds_read_b128 v[196:199], v139 offset:22528
	ds_read_b128 v[200:203], v139 offset:23552
	global_load_lds_dwordx4 v[204:205], off
	s_add_i32 m0, s30, 0x2000
	s_add_u32 s30, s36, 0x40000
	v_lshl_add_u64 v[206:207], s[36:37], 0, v[130:131]
	s_addc_u32 s31, s37, 0
	s_add_i32 s76, s77, s56
	global_load_lds_dwordx4 v[206:207], off
	v_lshl_add_u64 v[208:209], s[30:31], 0, v[128:129]
	s_mov_b32 m0, s76
	v_lshl_add_u64 v[210:211], s[40:41], 0, v[130:131]
	global_load_lds_dwordx4 v[208:209], off
	v_lshl_add_u64 v[208:209], s[30:31], 0, v[130:131]
	s_add_i32 m0, s76, 0x2000
	s_nop 0
	global_load_lds_dwordx4 v[208:209], off
	v_lshl_add_u64 v[208:209], s[40:41], 0, v[128:129]
	s_mov_b32 m0, s58
	s_nop 0
	global_load_lds_dwordx4 v[208:209], off
	s_mov_b32 m0, s60
	s_nop 0
	global_load_lds_dwordx4 v[210:211], off
	s_waitcnt vmcnt(8)
	s_waitcnt lgkmcnt(0)
	s_barrier
	s_waitcnt lgkmcnt(0)
	v_mfma_f32_16x16x32_bf16 v[60:63], v[140:143], v[172:175], v[60:63]
	v_mfma_f32_16x16x32_bf16 v[44:47], v[148:151], v[172:175], v[44:47]
	v_mfma_f32_16x16x32_bf16 v[56:59], v[140:143], v[180:183], v[56:59]
	v_mfma_f32_16x16x32_bf16 v[40:43], v[148:151], v[180:183], v[40:43]
	v_mfma_f32_16x16x32_bf16 v[52:55], v[140:143], v[188:191], v[52:55]
	v_mfma_f32_16x16x32_bf16 v[36:39], v[148:151], v[188:191], v[36:39]
	v_mfma_f32_16x16x32_bf16 v[48:51], v[140:143], v[196:199], v[48:51]
	v_mfma_f32_16x16x32_bf16 v[32:35], v[148:151], v[196:199], v[32:35]
	v_mfma_f32_16x16x32_bf16 v[60:63], v[144:147], v[176:179], v[60:63]
	v_mfma_f32_16x16x32_bf16 v[44:47], v[152:155], v[176:179], v[44:47]
	v_mfma_f32_16x16x32_bf16 v[56:59], v[144:147], v[184:187], v[56:59]
	v_mfma_f32_16x16x32_bf16 v[40:43], v[152:155], v[184:187], v[40:43]
	v_mfma_f32_16x16x32_bf16 v[52:55], v[144:147], v[192:195], v[52:55]
	v_mfma_f32_16x16x32_bf16 v[36:39], v[152:155], v[192:195], v[36:39]
	v_mfma_f32_16x16x32_bf16 v[48:51], v[144:147], v[200:203], v[48:51]
	v_mfma_f32_16x16x32_bf16 v[32:35], v[152:155], v[200:203], v[32:35]
	v_mfma_f32_16x16x32_bf16 v[28:31], v[156:159], v[172:175], v[28:31]
	v_mfma_f32_16x16x32_bf16 v[12:15], v[164:167], v[172:175], v[12:15]
	v_mfma_f32_16x16x32_bf16 v[24:27], v[156:159], v[180:183], v[24:27]
	v_mfma_f32_16x16x32_bf16 v[8:11], v[164:167], v[180:183], v[8:11]
	v_mfma_f32_16x16x32_bf16 v[20:23], v[156:159], v[188:191], v[20:23]
	v_mfma_f32_16x16x32_bf16 v[4:7], v[164:167], v[188:191], v[4:7]
	v_mfma_f32_16x16x32_bf16 v[16:19], v[156:159], v[196:199], v[16:19]
	v_mfma_f32_16x16x32_bf16 v[0:3], v[164:167], v[196:199], v[0:3]
	v_mfma_f32_16x16x32_bf16 v[28:31], v[160:163], v[176:179], v[28:31]
	v_mfma_f32_16x16x32_bf16 v[12:15], v[168:171], v[176:179], v[12:15]
	v_mfma_f32_16x16x32_bf16 v[24:27], v[160:163], v[184:187], v[24:27]
	v_mfma_f32_16x16x32_bf16 v[8:11], v[168:171], v[184:187], v[8:11]
	v_mfma_f32_16x16x32_bf16 v[20:23], v[160:163], v[192:195], v[20:23]
	v_mfma_f32_16x16x32_bf16 v[4:7], v[168:171], v[192:195], v[4:7]
	v_mfma_f32_16x16x32_bf16 v[16:19], v[160:163], v[200:203], v[16:19]
	v_mfma_f32_16x16x32_bf16 v[0:3], v[168:171], v[200:203], v[0:3]
	s_barrier
	s_add_i32 s76, 0, 0x18000
	s_add_i32 s77, 0, 0x1c000
	v_add_u32_e32 v152, s76, v138
	v_add_u32_e32 v168, s77, v138
	ds_read_b128 v[140:143], v152
	ds_read_b128 v[144:147], v152 offset:1024
	ds_read_b128 v[148:151], v152 offset:2048
	ds_read_b128 v[152:155], v152 offset:3072
	ds_read_b128 v[156:159], v168
	ds_read_b128 v[160:163], v168 offset:1024
	ds_read_b128 v[164:167], v168 offset:2048
	ds_read_b128 v[168:171], v168 offset:3072
	s_add_u32 s30, s40, 0x40000
	s_addc_u32 s31, s41, 0
	s_mov_b32 m0, s61
	v_lshl_add_u64 v[212:213], s[30:31], 0, v[128:129]
	ds_read_b128 v[172:175], v139 offset:32768
	ds_read_b128 v[176:179], v139 offset:33792
	ds_read_b128 v[180:183], v139 offset:34816
	ds_read_b128 v[184:187], v139 offset:35840
	ds_read_b128 v[188:191], v139 offset:36864
	ds_read_b128 v[192:195], v139 offset:37888
	ds_read_b128 v[196:199], v139 offset:38912
	ds_read_b128 v[200:203], v139 offset:39936
	global_load_lds_dwordx4 v[212:213], off
	v_lshl_add_u64 v[212:213], s[30:31], 0, v[130:131]
	s_mov_b32 m0, s62
	s_nop 0
	global_load_lds_dwordx4 v[212:213], off
	s_waitcnt vmcnt(8)
	s_waitcnt lgkmcnt(0)
	s_barrier
	s_waitcnt lgkmcnt(0)
	v_mfma_f32_16x16x32_bf16 v[124:127], v[140:143], v[172:175], v[124:127]
	v_mfma_f32_16x16x32_bf16 v[108:111], v[148:151], v[172:175], v[108:111]
	v_mfma_f32_16x16x32_bf16 v[120:123], v[140:143], v[180:183], v[120:123]
	v_mfma_f32_16x16x32_bf16 v[104:107], v[148:151], v[180:183], v[104:107]
	v_mfma_f32_16x16x32_bf16 v[116:119], v[140:143], v[188:191], v[116:119]
	v_mfma_f32_16x16x32_bf16 v[100:103], v[148:151], v[188:191], v[100:103]
	v_mfma_f32_16x16x32_bf16 v[112:115], v[140:143], v[196:199], v[112:115]
	v_mfma_f32_16x16x32_bf16 v[96:99], v[148:151], v[196:199], v[96:99]
	v_mfma_f32_16x16x32_bf16 v[124:127], v[144:147], v[176:179], v[124:127]
	v_mfma_f32_16x16x32_bf16 v[108:111], v[152:155], v[176:179], v[108:111]
	v_mfma_f32_16x16x32_bf16 v[120:123], v[144:147], v[184:187], v[120:123]
	v_mfma_f32_16x16x32_bf16 v[104:107], v[152:155], v[184:187], v[104:107]
	v_mfma_f32_16x16x32_bf16 v[116:119], v[144:147], v[192:195], v[116:119]
	v_mfma_f32_16x16x32_bf16 v[100:103], v[152:155], v[192:195], v[100:103]
	v_mfma_f32_16x16x32_bf16 v[112:115], v[144:147], v[200:203], v[112:115]
	v_mfma_f32_16x16x32_bf16 v[96:99], v[152:155], v[200:203], v[96:99]
	v_mfma_f32_16x16x32_bf16 v[92:95], v[156:159], v[172:175], v[92:95]
	v_mfma_f32_16x16x32_bf16 v[76:79], v[164:167], v[172:175], v[76:79]
	v_mfma_f32_16x16x32_bf16 v[88:91], v[156:159], v[180:183], v[88:91]
	v_mfma_f32_16x16x32_bf16 v[72:75], v[164:167], v[180:183], v[72:75]
	v_mfma_f32_16x16x32_bf16 v[84:87], v[156:159], v[188:191], v[84:87]
	v_mfma_f32_16x16x32_bf16 v[68:71], v[164:167], v[188:191], v[68:71]
	v_mfma_f32_16x16x32_bf16 v[80:83], v[156:159], v[196:199], v[80:83]
	v_mfma_f32_16x16x32_bf16 v[64:67], v[164:167], v[196:199], v[64:67]
	v_mfma_f32_16x16x32_bf16 v[92:95], v[160:163], v[176:179], v[92:95]
	v_mfma_f32_16x16x32_bf16 v[76:79], v[168:171], v[176:179], v[76:79]
	v_mfma_f32_16x16x32_bf16 v[88:91], v[160:163], v[184:187], v[88:91]
	v_mfma_f32_16x16x32_bf16 v[72:75], v[168:171], v[184:187], v[72:75]
	v_mfma_f32_16x16x32_bf16 v[84:87], v[160:163], v[192:195], v[84:87]
	v_mfma_f32_16x16x32_bf16 v[68:71], v[168:171], v[192:195], v[68:71]
	v_mfma_f32_16x16x32_bf16 v[80:83], v[160:163], v[200:203], v[80:83]
	v_mfma_f32_16x16x32_bf16 v[64:67], v[168:171], v[200:203], v[64:67]
	s_barrier
	s_add_i32 s30, s76, s56
	v_lshl_add_u64 v[204:205], v[204:205], 0, s[6:7]
	s_mov_b32 m0, s30
	ds_read_b128 v[172:175], v139 offset:49152
	ds_read_b128 v[176:179], v139 offset:50176
	ds_read_b128 v[180:183], v139 offset:51200
	ds_read_b128 v[184:187], v139 offset:52224
	ds_read_b128 v[188:191], v139 offset:53248
	ds_read_b128 v[192:195], v139 offset:54272
	ds_read_b128 v[196:199], v139 offset:55296
	ds_read_b128 v[200:203], v139 offset:56320
	global_load_lds_dwordx4 v[204:205], off
	s_add_i32 m0, s30, 0x2000
	s_add_u32 s30, s36, 0x40080
	v_lshl_add_u64 v[204:205], v[206:207], 0, s[6:7]
	s_addc_u32 s31, s37, 0
	s_add_i32 s36, s77, s56
	global_load_lds_dwordx4 v[204:205], off
	v_lshl_add_u64 v[204:205], s[30:31], 0, v[128:129]
	s_mov_b32 m0, s36
	s_nop 0
	global_load_lds_dwordx4 v[204:205], off
	v_lshl_add_u64 v[204:205], s[30:31], 0, v[130:131]
	s_add_i32 m0, s36, 0x2000
	s_nop 0
	global_load_lds_dwordx4 v[204:205], off
	v_lshl_add_u64 v[204:205], v[208:209], 0, s[6:7]
	s_mov_b32 m0, s63
	s_nop 0
	global_load_lds_dwordx4 v[204:205], off
	v_lshl_add_u64 v[204:205], v[210:211], 0, s[6:7]
	s_mov_b32 m0, s64
	s_nop 0
	global_load_lds_dwordx4 v[204:205], off
	s_waitcnt vmcnt(8)
	s_waitcnt lgkmcnt(0)
	s_barrier
	s_waitcnt lgkmcnt(0)
	v_mfma_f32_16x16x32_bf16 v[60:63], v[140:143], v[172:175], v[60:63]
	v_mfma_f32_16x16x32_bf16 v[44:47], v[148:151], v[172:175], v[44:47]
	v_mfma_f32_16x16x32_bf16 v[56:59], v[140:143], v[180:183], v[56:59]
	v_mfma_f32_16x16x32_bf16 v[40:43], v[148:151], v[180:183], v[40:43]
	v_mfma_f32_16x16x32_bf16 v[52:55], v[140:143], v[188:191], v[52:55]
	v_mfma_f32_16x16x32_bf16 v[36:39], v[148:151], v[188:191], v[36:39]
	v_mfma_f32_16x16x32_bf16 v[48:51], v[140:143], v[196:199], v[48:51]
	v_mfma_f32_16x16x32_bf16 v[32:35], v[148:151], v[196:199], v[32:35]
	v_mfma_f32_16x16x32_bf16 v[60:63], v[144:147], v[176:179], v[60:63]
	v_mfma_f32_16x16x32_bf16 v[44:47], v[152:155], v[176:179], v[44:47]
	v_mfma_f32_16x16x32_bf16 v[56:59], v[144:147], v[184:187], v[56:59]
	v_mfma_f32_16x16x32_bf16 v[40:43], v[152:155], v[184:187], v[40:43]
	v_mfma_f32_16x16x32_bf16 v[52:55], v[144:147], v[192:195], v[52:55]
	v_mfma_f32_16x16x32_bf16 v[36:39], v[152:155], v[192:195], v[36:39]
	v_mfma_f32_16x16x32_bf16 v[48:51], v[144:147], v[200:203], v[48:51]
	v_mfma_f32_16x16x32_bf16 v[32:35], v[152:155], v[200:203], v[32:35]
	v_mfma_f32_16x16x32_bf16 v[28:31], v[156:159], v[172:175], v[28:31]
	v_mfma_f32_16x16x32_bf16 v[12:15], v[164:167], v[172:175], v[12:15]
	v_mfma_f32_16x16x32_bf16 v[24:27], v[156:159], v[180:183], v[24:27]
	v_mfma_f32_16x16x32_bf16 v[8:11], v[164:167], v[180:183], v[8:11]
	v_mfma_f32_16x16x32_bf16 v[20:23], v[156:159], v[188:191], v[20:23]
	v_mfma_f32_16x16x32_bf16 v[4:7], v[164:167], v[188:191], v[4:7]
	v_mfma_f32_16x16x32_bf16 v[16:19], v[156:159], v[196:199], v[16:19]
	v_mfma_f32_16x16x32_bf16 v[0:3], v[164:167], v[196:199], v[0:3]
	v_mfma_f32_16x16x32_bf16 v[28:31], v[160:163], v[176:179], v[28:31]
	v_mfma_f32_16x16x32_bf16 v[12:15], v[168:171], v[176:179], v[12:15]
	v_mfma_f32_16x16x32_bf16 v[24:27], v[160:163], v[184:187], v[24:27]
	v_mfma_f32_16x16x32_bf16 v[8:11], v[168:171], v[184:187], v[8:11]
	v_mfma_f32_16x16x32_bf16 v[20:23], v[160:163], v[192:195], v[20:23]
	v_mfma_f32_16x16x32_bf16 v[4:7], v[168:171], v[192:195], v[4:7]
	v_mfma_f32_16x16x32_bf16 v[16:19], v[160:163], v[200:203], v[16:19]
	v_mfma_f32_16x16x32_bf16 v[0:3], v[168:171], v[200:203], v[0:3]
	s_barrier
	s_add_u32 s73, s73, 0x100
	s_addc_u32 s74, s74, 0
	s_cmp_ge_u32 s75, s92
	s_mov_b64 s[30:31], s[34:35]
	s_mov_b32 s36, s75
	s_cbranch_scc0 .LBB0_1501
	s_andn2_b64 vcc, exec, s[50:51]
	s_cbranch_vccnz .LBB0_1493
	v_mov_b32_e32 v0, 0
	s_mov_b32 s66, s22
	s_mov_b32 s65, s24
	s_mov_b64 s[18:19], s[28:29]
	s_mov_b64 s[20:21], s[26:27]
	s_mov_b32 s68, s70
	v_mov_b32_e32 v1, v0
	v_mov_b32_e32 v2, v0
	v_mov_b32_e32 v3, v0
	v_mov_b32_e32 v16, v0
	v_mov_b32_e32 v17, v0
	v_mov_b32_e32 v18, v0
	v_mov_b32_e32 v19, v0
	v_mov_b32_e32 v4, v0
	v_mov_b32_e32 v5, v0
	v_mov_b32_e32 v6, v0
	v_mov_b32_e32 v7, v0
	v_mov_b32_e32 v20, v0
	v_mov_b32_e32 v21, v0
	v_mov_b32_e32 v22, v0
	v_mov_b32_e32 v23, v0
	v_mov_b32_e32 v8, v0
	v_mov_b32_e32 v9, v0
	v_mov_b32_e32 v10, v0
	v_mov_b32_e32 v11, v0
	v_mov_b32_e32 v24, v0
	v_mov_b32_e32 v25, v0
	v_mov_b32_e32 v26, v0
	v_mov_b32_e32 v27, v0
	v_mov_b32_e32 v12, v0
	v_mov_b32_e32 v13, v0
	v_mov_b32_e32 v14, v0
	v_mov_b32_e32 v15, v0
	v_mov_b32_e32 v28, v0
	v_mov_b32_e32 v29, v0
	v_mov_b32_e32 v30, v0
	v_mov_b32_e32 v31, v0
	v_mov_b32_e32 v32, v0
	v_mov_b32_e32 v33, v0
	v_mov_b32_e32 v34, v0
	v_mov_b32_e32 v35, v0
	v_mov_b32_e32 v48, v0
	v_mov_b32_e32 v49, v0
	v_mov_b32_e32 v50, v0
	v_mov_b32_e32 v51, v0
	v_mov_b32_e32 v36, v0
	v_mov_b32_e32 v37, v0
	v_mov_b32_e32 v38, v0
	v_mov_b32_e32 v39, v0
	v_mov_b32_e32 v52, v0
	v_mov_b32_e32 v53, v0
	v_mov_b32_e32 v54, v0
	v_mov_b32_e32 v55, v0
	v_mov_b32_e32 v40, v0
	v_mov_b32_e32 v41, v0
	v_mov_b32_e32 v42, v0
	v_mov_b32_e32 v43, v0
	v_mov_b32_e32 v56, v0
	v_mov_b32_e32 v57, v0
	v_mov_b32_e32 v58, v0
	v_mov_b32_e32 v59, v0
	v_mov_b32_e32 v44, v0
	v_mov_b32_e32 v45, v0
	v_mov_b32_e32 v46, v0
	v_mov_b32_e32 v47, v0
	v_mov_b32_e32 v60, v0
	v_mov_b32_e32 v61, v0
	v_mov_b32_e32 v62, v0
	v_mov_b32_e32 v63, v0
	v_mov_b32_e32 v64, v0
	v_mov_b32_e32 v65, v0
	v_mov_b32_e32 v66, v0
	v_mov_b32_e32 v67, v0
	v_mov_b32_e32 v80, v0
	v_mov_b32_e32 v81, v0
	v_mov_b32_e32 v82, v0
	v_mov_b32_e32 v83, v0
	v_mov_b32_e32 v68, v0
	v_mov_b32_e32 v69, v0
	v_mov_b32_e32 v70, v0
	v_mov_b32_e32 v71, v0
	v_mov_b32_e32 v84, v0
	v_mov_b32_e32 v85, v0
	v_mov_b32_e32 v86, v0
	v_mov_b32_e32 v87, v0
	v_mov_b32_e32 v72, v0
	v_mov_b32_e32 v73, v0
	v_mov_b32_e32 v74, v0
	v_mov_b32_e32 v75, v0
	v_mov_b32_e32 v88, v0
	v_mov_b32_e32 v89, v0
	v_mov_b32_e32 v90, v0
	v_mov_b32_e32 v91, v0
	v_mov_b32_e32 v76, v0
	v_mov_b32_e32 v77, v0
	v_mov_b32_e32 v78, v0
	v_mov_b32_e32 v79, v0
	v_mov_b32_e32 v92, v0
	v_mov_b32_e32 v93, v0
	v_mov_b32_e32 v94, v0
	v_mov_b32_e32 v95, v0
	v_mov_b32_e32 v96, v0
	v_mov_b32_e32 v97, v0
	v_mov_b32_e32 v98, v0
	v_mov_b32_e32 v99, v0
	v_mov_b32_e32 v112, v0
	v_mov_b32_e32 v113, v0
	v_mov_b32_e32 v114, v0
	v_mov_b32_e32 v115, v0
	v_mov_b32_e32 v100, v0
	v_mov_b32_e32 v101, v0
	v_mov_b32_e32 v102, v0
	v_mov_b32_e32 v103, v0
	v_mov_b32_e32 v116, v0
	v_mov_b32_e32 v117, v0
	v_mov_b32_e32 v118, v0
	v_mov_b32_e32 v119, v0
	v_mov_b32_e32 v104, v0
	v_mov_b32_e32 v105, v0
	v_mov_b32_e32 v106, v0
	v_mov_b32_e32 v107, v0
	v_mov_b32_e32 v120, v0
	v_mov_b32_e32 v121, v0
	v_mov_b32_e32 v122, v0
	v_mov_b32_e32 v123, v0
	v_mov_b32_e32 v108, v0
	v_mov_b32_e32 v109, v0
	v_mov_b32_e32 v110, v0
	v_mov_b32_e32 v111, v0
	v_mov_b32_e32 v124, v0
	v_mov_b32_e32 v125, v0
	v_mov_b32_e32 v126, v0
	v_mov_b32_e32 v127, v0
	s_branch .LBB0_1493

.LBB0_1766:
	s_add_u32 s34, s30, 0xfffc0080
	s_addc_u32 s35, s31, -1
	s_add_i32 s70, 0, 0x10000
	s_cmp_eq_u32 s66, 12
	s_cselect_b32 s37, s25, s35
	s_cselect_b32 s36, s62, s34
	v_add_u32_e32 v140, s70, v144
	s_cselect_b32 s35, s23, s65
	s_cselect_b32 s34, s63, s64
	s_add_i32 s72, 0, 0x14000
	ds_read_b128 v[146:149], v140
	ds_read_b128 v[150:153], v140 offset:1024
	ds_read_b128 v[154:157], v140 offset:2048
	ds_read_b128 v[158:161], v140 offset:3072
	v_add_u32_e32 v140, s72, v144
	ds_read_b128 v[162:165], v140
	ds_read_b128 v[166:169], v140 offset:1024
	ds_read_b128 v[170:173], v140 offset:2048
	ds_read_b128 v[174:177], v140 offset:3072
	v_lshl_add_u64 v[140:141], s[30:31], 0, v[136:137]
	s_add_i32 m0, s50, 0xc000
	ds_read_b128 v[178:181], v145
	ds_read_b128 v[182:185], v145 offset:1024
	ds_read_b128 v[186:189], v145 offset:2048
	ds_read_b128 v[190:193], v145 offset:3072
	ds_read_b128 v[194:197], v145 offset:4096
	ds_read_b128 v[198:201], v145 offset:5120
	ds_read_b128 v[202:205], v145 offset:6144
	ds_read_b128 v[206:209], v145 offset:7168
	global_load_lds_dwordx4 v[140:141], off
	v_lshl_add_u64 v[140:141], s[30:31], 0, v[138:139]
	s_add_i32 m0, s50, 0xe000
	s_nop 0
	global_load_lds_dwordx4 v[140:141], off
	s_waitcnt vmcnt(8)
	s_waitcnt lgkmcnt(0)
	s_barrier
	s_waitcnt lgkmcnt(0)
	v_mfma_f32_16x16x32_bf16 v[124:127], v[146:149], v[178:181], v[124:127]
	v_mfma_f32_16x16x32_bf16 v[120:123], v[154:157], v[178:181], v[120:123]
	v_mfma_f32_16x16x32_bf16 v[108:111], v[146:149], v[186:189], v[108:111]
	v_mfma_f32_16x16x32_bf16 v[104:107], v[154:157], v[186:189], v[104:107]
	v_mfma_f32_16x16x32_bf16 v[92:95], v[146:149], v[194:197], v[92:95]
	v_mfma_f32_16x16x32_bf16 v[88:91], v[154:157], v[194:197], v[88:91]
	v_mfma_f32_16x16x32_bf16 v[76:79], v[146:149], v[202:205], v[76:79]
	v_mfma_f32_16x16x32_bf16 v[72:75], v[154:157], v[202:205], v[72:75]
	v_mfma_f32_16x16x32_bf16 v[124:127], v[150:153], v[182:185], v[124:127]
	v_mfma_f32_16x16x32_bf16 v[120:123], v[158:161], v[182:185], v[120:123]
	v_mfma_f32_16x16x32_bf16 v[108:111], v[150:153], v[190:193], v[108:111]
	v_mfma_f32_16x16x32_bf16 v[104:107], v[158:161], v[190:193], v[104:107]
	v_mfma_f32_16x16x32_bf16 v[92:95], v[150:153], v[198:201], v[92:95]
	v_mfma_f32_16x16x32_bf16 v[88:91], v[158:161], v[198:201], v[88:91]
	v_mfma_f32_16x16x32_bf16 v[76:79], v[150:153], v[206:209], v[76:79]
	v_mfma_f32_16x16x32_bf16 v[72:75], v[158:161], v[206:209], v[72:75]
	v_mfma_f32_16x16x32_bf16 v[116:119], v[162:165], v[178:181], v[116:119]
	v_mfma_f32_16x16x32_bf16 v[112:115], v[170:173], v[178:181], v[112:115]
	v_mfma_f32_16x16x32_bf16 v[100:103], v[162:165], v[186:189], v[100:103]
	v_mfma_f32_16x16x32_bf16 v[96:99], v[170:173], v[186:189], v[96:99]
	v_mfma_f32_16x16x32_bf16 v[84:87], v[162:165], v[194:197], v[84:87]
	v_mfma_f32_16x16x32_bf16 v[80:83], v[170:173], v[194:197], v[80:83]
	v_mfma_f32_16x16x32_bf16 v[68:71], v[162:165], v[202:205], v[68:71]
	v_mfma_f32_16x16x32_bf16 v[64:67], v[170:173], v[202:205], v[64:67]
	v_mfma_f32_16x16x32_bf16 v[116:119], v[166:169], v[182:185], v[116:119]
	v_mfma_f32_16x16x32_bf16 v[112:115], v[174:177], v[182:185], v[112:115]
	v_mfma_f32_16x16x32_bf16 v[100:103], v[166:169], v[190:193], v[100:103]
	v_mfma_f32_16x16x32_bf16 v[96:99], v[174:177], v[190:193], v[96:99]
	v_mfma_f32_16x16x32_bf16 v[84:87], v[166:169], v[198:201], v[84:87]
	v_mfma_f32_16x16x32_bf16 v[80:83], v[174:177], v[198:201], v[80:83]
	v_mfma_f32_16x16x32_bf16 v[68:71], v[166:169], v[206:209], v[68:71]
	v_mfma_f32_16x16x32_bf16 v[64:67], v[174:177], v[206:209], v[64:67]
	s_barrier
	s_add_i32 s70, s70, s41
	v_lshl_add_u64 v[140:141], s[34:35], 0, v[128:129]
	s_mov_b32 m0, s70
	ds_read_b128 v[178:181], v145 offset:16384
	ds_read_b128 v[182:185], v145 offset:17408
	ds_read_b128 v[186:189], v145 offset:18432
	ds_read_b128 v[190:193], v145 offset:19456
	ds_read_b128 v[194:197], v145 offset:20480
	ds_read_b128 v[198:201], v145 offset:21504
	ds_read_b128 v[202:205], v145 offset:22528
	ds_read_b128 v[206:209], v145 offset:23552
	global_load_lds_dwordx4 v[140:141], off
	s_add_i32 m0, s70, 0x2000
	s_add_u32 s70, s34, 0x40000
	v_lshl_add_u64 v[210:211], s[34:35], 0, v[130:131]
	s_addc_u32 s71, s35, 0
	s_add_i32 s72, s72, s41
	global_load_lds_dwordx4 v[210:211], off
	v_lshl_add_u64 v[212:213], s[70:71], 0, v[128:129]
	s_mov_b32 m0, s72
	v_lshl_add_u64 v[214:215], s[36:37], 0, v[132:133]
	global_load_lds_dwordx4 v[212:213], off
	v_lshl_add_u64 v[212:213], s[70:71], 0, v[130:131]
	s_add_i32 m0, s72, 0x2000
	s_nop 0
	global_load_lds_dwordx4 v[212:213], off
	v_lshl_add_u64 v[212:213], s[36:37], 0, v[134:135]
	s_mov_b32 m0, s50
	s_nop 0
	global_load_lds_dwordx4 v[212:213], off
	s_mov_b32 m0, s51
	s_nop 0
	global_load_lds_dwordx4 v[214:215], off
	s_waitcnt vmcnt(8)
	s_waitcnt lgkmcnt(0)
	s_barrier
	s_waitcnt lgkmcnt(0)
	v_mfma_f32_16x16x32_bf16 v[60:63], v[146:149], v[178:181], v[60:63]
	v_mfma_f32_16x16x32_bf16 v[56:59], v[154:157], v[178:181], v[56:59]
	v_mfma_f32_16x16x32_bf16 v[44:47], v[146:149], v[186:189], v[44:47]
	v_mfma_f32_16x16x32_bf16 v[40:43], v[154:157], v[186:189], v[40:43]
	v_mfma_f32_16x16x32_bf16 v[28:31], v[146:149], v[194:197], v[28:31]
	v_mfma_f32_16x16x32_bf16 v[24:27], v[154:157], v[194:197], v[24:27]
	v_mfma_f32_16x16x32_bf16 v[12:15], v[146:149], v[202:205], v[12:15]
	v_mfma_f32_16x16x32_bf16 v[8:11], v[154:157], v[202:205], v[8:11]
	v_mfma_f32_16x16x32_bf16 v[60:63], v[150:153], v[182:185], v[60:63]
	v_mfma_f32_16x16x32_bf16 v[56:59], v[158:161], v[182:185], v[56:59]
	v_mfma_f32_16x16x32_bf16 v[44:47], v[150:153], v[190:193], v[44:47]
	v_mfma_f32_16x16x32_bf16 v[40:43], v[158:161], v[190:193], v[40:43]
	v_mfma_f32_16x16x32_bf16 v[28:31], v[150:153], v[198:201], v[28:31]
	v_mfma_f32_16x16x32_bf16 v[24:27], v[158:161], v[198:201], v[24:27]
	v_mfma_f32_16x16x32_bf16 v[12:15], v[150:153], v[206:209], v[12:15]
	v_mfma_f32_16x16x32_bf16 v[8:11], v[158:161], v[206:209], v[8:11]
	v_mfma_f32_16x16x32_bf16 v[52:55], v[162:165], v[178:181], v[52:55]
	v_mfma_f32_16x16x32_bf16 v[48:51], v[170:173], v[178:181], v[48:51]
	v_mfma_f32_16x16x32_bf16 v[36:39], v[162:165], v[186:189], v[36:39]
	v_mfma_f32_16x16x32_bf16 v[32:35], v[170:173], v[186:189], v[32:35]
	v_mfma_f32_16x16x32_bf16 v[20:23], v[162:165], v[194:197], v[20:23]
	v_mfma_f32_16x16x32_bf16 v[16:19], v[170:173], v[194:197], v[16:19]
	v_mfma_f32_16x16x32_bf16 v[4:7], v[162:165], v[202:205], v[4:7]
	v_mfma_f32_16x16x32_bf16 v[0:3], v[170:173], v[202:205], v[0:3]
	v_mfma_f32_16x16x32_bf16 v[52:55], v[166:169], v[182:185], v[52:55]
	v_mfma_f32_16x16x32_bf16 v[48:51], v[174:177], v[182:185], v[48:51]
	v_mfma_f32_16x16x32_bf16 v[36:39], v[166:169], v[190:193], v[36:39]
	v_mfma_f32_16x16x32_bf16 v[32:35], v[174:177], v[190:193], v[32:35]
	v_mfma_f32_16x16x32_bf16 v[20:23], v[166:169], v[198:201], v[20:23]
	v_mfma_f32_16x16x32_bf16 v[16:19], v[174:177], v[198:201], v[16:19]
	v_mfma_f32_16x16x32_bf16 v[4:7], v[166:169], v[206:209], v[4:7]
	v_mfma_f32_16x16x32_bf16 v[0:3], v[174:177], v[206:209], v[0:3]
	s_barrier
	s_add_i32 s70, 0, 0x18000
	s_add_i32 s71, 0, 0x1c000
	v_add_u32_e32 v158, s70, v144
	v_add_u32_e32 v174, s71, v144
	ds_read_b128 v[146:149], v158
	ds_read_b128 v[150:153], v158 offset:1024
	ds_read_b128 v[154:157], v158 offset:2048
	ds_read_b128 v[158:161], v158 offset:3072
	ds_read_b128 v[162:165], v174
	ds_read_b128 v[166:169], v174 offset:1024
	ds_read_b128 v[170:173], v174 offset:2048
	ds_read_b128 v[174:177], v174 offset:3072
	s_add_u32 s36, s36, 0x40000
	s_addc_u32 s37, s37, 0
	s_mov_b32 m0, s54
	v_lshl_add_u64 v[216:217], s[36:37], 0, v[134:135]
	ds_read_b128 v[178:181], v145 offset:32768
	ds_read_b128 v[182:185], v145 offset:33792
	ds_read_b128 v[186:189], v145 offset:34816
	ds_read_b128 v[190:193], v145 offset:35840
	ds_read_b128 v[194:197], v145 offset:36864
	ds_read_b128 v[198:201], v145 offset:37888
	ds_read_b128 v[202:205], v145 offset:38912
	ds_read_b128 v[206:209], v145 offset:39936
	global_load_lds_dwordx4 v[216:217], off
	v_lshl_add_u64 v[216:217], s[36:37], 0, v[132:133]
	s_mov_b32 m0, s55
	s_nop 0
	global_load_lds_dwordx4 v[216:217], off
	s_waitcnt vmcnt(8)
	s_waitcnt lgkmcnt(0)
	s_barrier
	s_waitcnt lgkmcnt(0)
	v_mfma_f32_16x16x32_bf16 v[124:127], v[146:149], v[178:181], v[124:127]
	v_mfma_f32_16x16x32_bf16 v[120:123], v[154:157], v[178:181], v[120:123]
	v_mfma_f32_16x16x32_bf16 v[108:111], v[146:149], v[186:189], v[108:111]
	v_mfma_f32_16x16x32_bf16 v[104:107], v[154:157], v[186:189], v[104:107]
	v_mfma_f32_16x16x32_bf16 v[92:95], v[146:149], v[194:197], v[92:95]
	v_mfma_f32_16x16x32_bf16 v[88:91], v[154:157], v[194:197], v[88:91]
	v_mfma_f32_16x16x32_bf16 v[76:79], v[146:149], v[202:205], v[76:79]
	v_mfma_f32_16x16x32_bf16 v[72:75], v[154:157], v[202:205], v[72:75]
	v_mfma_f32_16x16x32_bf16 v[124:127], v[150:153], v[182:185], v[124:127]
	v_mfma_f32_16x16x32_bf16 v[120:123], v[158:161], v[182:185], v[120:123]
	v_mfma_f32_16x16x32_bf16 v[108:111], v[150:153], v[190:193], v[108:111]
	v_mfma_f32_16x16x32_bf16 v[104:107], v[158:161], v[190:193], v[104:107]
	v_mfma_f32_16x16x32_bf16 v[92:95], v[150:153], v[198:201], v[92:95]
	v_mfma_f32_16x16x32_bf16 v[88:91], v[158:161], v[198:201], v[88:91]
	v_mfma_f32_16x16x32_bf16 v[76:79], v[150:153], v[206:209], v[76:79]
	v_mfma_f32_16x16x32_bf16 v[72:75], v[158:161], v[206:209], v[72:75]
	v_mfma_f32_16x16x32_bf16 v[116:119], v[162:165], v[178:181], v[116:119]
	v_mfma_f32_16x16x32_bf16 v[112:115], v[170:173], v[178:181], v[112:115]
	v_mfma_f32_16x16x32_bf16 v[100:103], v[162:165], v[186:189], v[100:103]
	v_mfma_f32_16x16x32_bf16 v[96:99], v[170:173], v[186:189], v[96:99]
	v_mfma_f32_16x16x32_bf16 v[84:87], v[162:165], v[194:197], v[84:87]
	v_mfma_f32_16x16x32_bf16 v[80:83], v[170:173], v[194:197], v[80:83]
	v_mfma_f32_16x16x32_bf16 v[68:71], v[162:165], v[202:205], v[68:71]
	v_mfma_f32_16x16x32_bf16 v[64:67], v[170:173], v[202:205], v[64:67]
	v_mfma_f32_16x16x32_bf16 v[116:119], v[166:169], v[182:185], v[116:119]
	v_mfma_f32_16x16x32_bf16 v[112:115], v[174:177], v[182:185], v[112:115]
	v_mfma_f32_16x16x32_bf16 v[100:103], v[166:169], v[190:193], v[100:103]
	v_mfma_f32_16x16x32_bf16 v[96:99], v[174:177], v[190:193], v[96:99]
	v_mfma_f32_16x16x32_bf16 v[84:87], v[166:169], v[198:201], v[84:87]
	v_mfma_f32_16x16x32_bf16 v[80:83], v[174:177], v[198:201], v[80:83]
	v_mfma_f32_16x16x32_bf16 v[68:71], v[166:169], v[206:209], v[68:71]
	v_mfma_f32_16x16x32_bf16 v[64:67], v[174:177], v[206:209], v[64:67]
	s_barrier
	s_add_i32 s36, s70, s41
	v_lshl_add_u64 v[140:141], v[140:141], 0, s[6:7]
	s_mov_b32 m0, s36
	ds_read_b128 v[178:181], v145 offset:49152
	ds_read_b128 v[182:185], v145 offset:50176
	ds_read_b128 v[186:189], v145 offset:51200
	ds_read_b128 v[190:193], v145 offset:52224
	ds_read_b128 v[194:197], v145 offset:53248
	ds_read_b128 v[198:201], v145 offset:54272
	ds_read_b128 v[202:205], v145 offset:55296
	ds_read_b128 v[206:209], v145 offset:56320
	global_load_lds_dwordx4 v[140:141], off
	s_add_i32 m0, s36, 0x2000
	s_add_u32 s34, s34, 0x40080
	v_lshl_add_u64 v[140:141], v[210:211], 0, s[6:7]
	s_addc_u32 s35, s35, 0
	s_add_i32 s36, s71, s41
	global_load_lds_dwordx4 v[140:141], off
	v_lshl_add_u64 v[140:141], s[34:35], 0, v[128:129]
	s_mov_b32 m0, s36
	s_nop 0
	global_load_lds_dwordx4 v[140:141], off
	v_lshl_add_u64 v[140:141], s[34:35], 0, v[130:131]
	s_add_i32 m0, s36, 0x2000
	s_nop 0
	global_load_lds_dwordx4 v[140:141], off
	v_lshl_add_u64 v[140:141], v[212:213], 0, s[6:7]
	s_mov_b32 m0, s57
	s_nop 0
	global_load_lds_dwordx4 v[140:141], off
	v_lshl_add_u64 v[140:141], v[214:215], 0, s[6:7]
	s_mov_b32 m0, s58
	s_nop 0
	global_load_lds_dwordx4 v[140:141], off
	s_waitcnt vmcnt(8)
	s_waitcnt lgkmcnt(0)
	s_barrier
	s_waitcnt lgkmcnt(0)
	v_mfma_f32_16x16x32_bf16 v[60:63], v[146:149], v[178:181], v[60:63]
	v_mfma_f32_16x16x32_bf16 v[56:59], v[154:157], v[178:181], v[56:59]
	v_mfma_f32_16x16x32_bf16 v[44:47], v[146:149], v[186:189], v[44:47]
	v_mfma_f32_16x16x32_bf16 v[40:43], v[154:157], v[186:189], v[40:43]
	v_mfma_f32_16x16x32_bf16 v[28:31], v[146:149], v[194:197], v[28:31]
	v_mfma_f32_16x16x32_bf16 v[24:27], v[154:157], v[194:197], v[24:27]
	v_mfma_f32_16x16x32_bf16 v[12:15], v[146:149], v[202:205], v[12:15]
	v_mfma_f32_16x16x32_bf16 v[8:11], v[154:157], v[202:205], v[8:11]
	v_mfma_f32_16x16x32_bf16 v[60:63], v[150:153], v[182:185], v[60:63]
	v_mfma_f32_16x16x32_bf16 v[56:59], v[158:161], v[182:185], v[56:59]
	v_mfma_f32_16x16x32_bf16 v[44:47], v[150:153], v[190:193], v[44:47]
	v_mfma_f32_16x16x32_bf16 v[40:43], v[158:161], v[190:193], v[40:43]
	v_mfma_f32_16x16x32_bf16 v[28:31], v[150:153], v[198:201], v[28:31]
	v_mfma_f32_16x16x32_bf16 v[24:27], v[158:161], v[198:201], v[24:27]
	v_mfma_f32_16x16x32_bf16 v[12:15], v[150:153], v[206:209], v[12:15]
	v_mfma_f32_16x16x32_bf16 v[8:11], v[158:161], v[206:209], v[8:11]
	v_mfma_f32_16x16x32_bf16 v[52:55], v[162:165], v[178:181], v[52:55]
	v_mfma_f32_16x16x32_bf16 v[48:51], v[170:173], v[178:181], v[48:51]
	v_mfma_f32_16x16x32_bf16 v[36:39], v[162:165], v[186:189], v[36:39]
	v_mfma_f32_16x16x32_bf16 v[32:35], v[170:173], v[186:189], v[32:35]
	v_mfma_f32_16x16x32_bf16 v[20:23], v[162:165], v[194:197], v[20:23]
	v_mfma_f32_16x16x32_bf16 v[16:19], v[170:173], v[194:197], v[16:19]
	v_mfma_f32_16x16x32_bf16 v[4:7], v[162:165], v[202:205], v[4:7]
	v_mfma_f32_16x16x32_bf16 v[0:3], v[170:173], v[202:205], v[0:3]
	v_mfma_f32_16x16x32_bf16 v[52:55], v[166:169], v[182:185], v[52:55]
	v_mfma_f32_16x16x32_bf16 v[48:51], v[174:177], v[182:185], v[48:51]
	v_mfma_f32_16x16x32_bf16 v[36:39], v[166:169], v[190:193], v[36:39]
	v_mfma_f32_16x16x32_bf16 v[32:35], v[174:177], v[190:193], v[32:35]
	v_mfma_f32_16x16x32_bf16 v[20:23], v[166:169], v[198:201], v[20:23]
	v_mfma_f32_16x16x32_bf16 v[16:19], v[174:177], v[198:201], v[16:19]
	v_mfma_f32_16x16x32_bf16 v[4:7], v[166:169], v[206:209], v[4:7]
	v_mfma_f32_16x16x32_bf16 v[0:3], v[174:177], v[206:209], v[0:3]
	s_barrier
	s_add_i32 s66, s66, 2
	s_add_u32 s30, s30, 0x100
	s_addc_u32 s31, s31, 0
	s_add_u32 s64, s64, 0x100
	s_addc_u32 s65, s65, 0
	s_cmp_gt_u32 s66, 13
	s_cbranch_scc0 .LBB0_1766
	s_and_b64 vcc, exec, s[18:19]
	s_cbranch_vccz .LBB0_1769
	s_barrier

.LBB0_1859:
	s_add_i32 s73, s36, 2
	s_add_u32 s34, s30, 0x100
	s_addc_u32 s35, s31, 0
	s_add_i32 s74, 0, 0x10000
	s_cmp_eq_u32 s0, s36
	s_cselect_b32 s41, s25, s35
	s_cselect_b32 s40, s68, s34
	s_cselect_b32 s37, s23, s72
	s_cselect_b32 s36, s70, s71
	s_add_i32 s75, 0, 0x14000
	v_add_u32_e32 v152, s74, v138
	v_add_u32_e32 v168, s75, v138
	ds_read_b128 v[140:143], v152
	ds_read_b128 v[144:147], v152 offset:1024
	ds_read_b128 v[148:151], v152 offset:2048
	ds_read_b128 v[152:155], v152 offset:3072
	ds_read_b128 v[156:159], v168
	ds_read_b128 v[160:163], v168 offset:1024
	ds_read_b128 v[164:167], v168 offset:2048
	ds_read_b128 v[168:171], v168 offset:3072
	v_lshl_add_u64 v[204:205], s[30:31], 0, v[132:133]
	s_add_i32 m0, s56, 0xc000
	ds_read_b128 v[172:175], v139
	ds_read_b128 v[176:179], v139 offset:1024
	ds_read_b128 v[180:183], v139 offset:2048
	ds_read_b128 v[184:187], v139 offset:3072
	ds_read_b128 v[188:191], v139 offset:4096
	ds_read_b128 v[192:195], v139 offset:5120
	ds_read_b128 v[196:199], v139 offset:6144
	ds_read_b128 v[200:203], v139 offset:7168
	global_load_lds_dwordx4 v[204:205], off
	v_lshl_add_u64 v[204:205], s[30:31], 0, v[134:135]
	s_add_i32 m0, s56, 0xe000
	s_nop 0
	global_load_lds_dwordx4 v[204:205], off
	s_waitcnt vmcnt(8)
	s_waitcnt lgkmcnt(0)
	s_barrier
	s_waitcnt lgkmcnt(0)
	v_mfma_f32_16x16x32_bf16 v[124:127], v[140:143], v[172:175], v[124:127]
	v_mfma_f32_16x16x32_bf16 v[108:111], v[148:151], v[172:175], v[108:111]
	v_mfma_f32_16x16x32_bf16 v[120:123], v[140:143], v[180:183], v[120:123]
	v_mfma_f32_16x16x32_bf16 v[104:107], v[148:151], v[180:183], v[104:107]
	v_mfma_f32_16x16x32_bf16 v[116:119], v[140:143], v[188:191], v[116:119]
	v_mfma_f32_16x16x32_bf16 v[100:103], v[148:151], v[188:191], v[100:103]
	v_mfma_f32_16x16x32_bf16 v[112:115], v[140:143], v[196:199], v[112:115]
	v_mfma_f32_16x16x32_bf16 v[96:99], v[148:151], v[196:199], v[96:99]
	v_mfma_f32_16x16x32_bf16 v[124:127], v[144:147], v[176:179], v[124:127]
	v_mfma_f32_16x16x32_bf16 v[108:111], v[152:155], v[176:179], v[108:111]
	v_mfma_f32_16x16x32_bf16 v[120:123], v[144:147], v[184:187], v[120:123]
	v_mfma_f32_16x16x32_bf16 v[104:107], v[152:155], v[184:187], v[104:107]
	v_mfma_f32_16x16x32_bf16 v[116:119], v[144:147], v[192:195], v[116:119]
	v_mfma_f32_16x16x32_bf16 v[100:103], v[152:155], v[192:195], v[100:103]
	v_mfma_f32_16x16x32_bf16 v[112:115], v[144:147], v[200:203], v[112:115]
	v_mfma_f32_16x16x32_bf16 v[96:99], v[152:155], v[200:203], v[96:99]
	v_mfma_f32_16x16x32_bf16 v[92:95], v[156:159], v[172:175], v[92:95]
	v_mfma_f32_16x16x32_bf16 v[76:79], v[164:167], v[172:175], v[76:79]
	v_mfma_f32_16x16x32_bf16 v[88:91], v[156:159], v[180:183], v[88:91]
	v_mfma_f32_16x16x32_bf16 v[72:75], v[164:167], v[180:183], v[72:75]
	v_mfma_f32_16x16x32_bf16 v[84:87], v[156:159], v[188:191], v[84:87]
	v_mfma_f32_16x16x32_bf16 v[68:71], v[164:167], v[188:191], v[68:71]
	v_mfma_f32_16x16x32_bf16 v[80:83], v[156:159], v[196:199], v[80:83]
	v_mfma_f32_16x16x32_bf16 v[64:67], v[164:167], v[196:199], v[64:67]
	v_mfma_f32_16x16x32_bf16 v[92:95], v[160:163], v[176:179], v[92:95]
	v_mfma_f32_16x16x32_bf16 v[76:79], v[168:171], v[176:179], v[76:79]
	v_mfma_f32_16x16x32_bf16 v[88:91], v[160:163], v[184:187], v[88:91]
	v_mfma_f32_16x16x32_bf16 v[72:75], v[168:171], v[184:187], v[72:75]
	v_mfma_f32_16x16x32_bf16 v[84:87], v[160:163], v[192:195], v[84:87]
	v_mfma_f32_16x16x32_bf16 v[68:71], v[168:171], v[192:195], v[68:71]
	v_mfma_f32_16x16x32_bf16 v[80:83], v[160:163], v[200:203], v[80:83]
	v_mfma_f32_16x16x32_bf16 v[64:67], v[168:171], v[200:203], v[64:67]
	s_barrier
	s_add_i32 s30, s74, s54
	v_lshl_add_u64 v[204:205], s[36:37], 0, v[128:129]
	s_mov_b32 m0, s30
	ds_read_b128 v[172:175], v139 offset:16384
	ds_read_b128 v[176:179], v139 offset:17408
	ds_read_b128 v[180:183], v139 offset:18432
	ds_read_b128 v[184:187], v139 offset:19456
	ds_read_b128 v[188:191], v139 offset:20480
	ds_read_b128 v[192:195], v139 offset:21504
	ds_read_b128 v[196:199], v139 offset:22528
	ds_read_b128 v[200:203], v139 offset:23552
	global_load_lds_dwordx4 v[204:205], off
	s_add_i32 m0, s30, 0x2000
	s_add_u32 s30, s36, 0x100000
	v_lshl_add_u64 v[206:207], s[36:37], 0, v[130:131]
	s_addc_u32 s31, s37, 0
	s_add_i32 s74, s75, s54
	global_load_lds_dwordx4 v[206:207], off
	v_lshl_add_u64 v[208:209], s[30:31], 0, v[128:129]
	s_mov_b32 m0, s74
	v_lshl_add_u64 v[210:211], s[40:41], 0, v[130:131]
	global_load_lds_dwordx4 v[208:209], off
	v_lshl_add_u64 v[208:209], s[30:31], 0, v[130:131]
	s_add_i32 m0, s74, 0x2000
	s_nop 0
	global_load_lds_dwordx4 v[208:209], off
	v_lshl_add_u64 v[208:209], s[40:41], 0, v[128:129]
	s_mov_b32 m0, s56
	s_nop 0
	global_load_lds_dwordx4 v[208:209], off
	s_mov_b32 m0, s58
	s_nop 0
	global_load_lds_dwordx4 v[210:211], off
	s_waitcnt vmcnt(8)
	s_waitcnt lgkmcnt(0)
	s_barrier
	s_waitcnt lgkmcnt(0)
	v_mfma_f32_16x16x32_bf16 v[60:63], v[140:143], v[172:175], v[60:63]
	v_mfma_f32_16x16x32_bf16 v[44:47], v[148:151], v[172:175], v[44:47]
	v_mfma_f32_16x16x32_bf16 v[56:59], v[140:143], v[180:183], v[56:59]
	v_mfma_f32_16x16x32_bf16 v[40:43], v[148:151], v[180:183], v[40:43]
	v_mfma_f32_16x16x32_bf16 v[52:55], v[140:143], v[188:191], v[52:55]
	v_mfma_f32_16x16x32_bf16 v[36:39], v[148:151], v[188:191], v[36:39]
	v_mfma_f32_16x16x32_bf16 v[48:51], v[140:143], v[196:199], v[48:51]
	v_mfma_f32_16x16x32_bf16 v[32:35], v[148:151], v[196:199], v[32:35]
	v_mfma_f32_16x16x32_bf16 v[60:63], v[144:147], v[176:179], v[60:63]
	v_mfma_f32_16x16x32_bf16 v[44:47], v[152:155], v[176:179], v[44:47]
	v_mfma_f32_16x16x32_bf16 v[56:59], v[144:147], v[184:187], v[56:59]
	v_mfma_f32_16x16x32_bf16 v[40:43], v[152:155], v[184:187], v[40:43]
	v_mfma_f32_16x16x32_bf16 v[52:55], v[144:147], v[192:195], v[52:55]
	v_mfma_f32_16x16x32_bf16 v[36:39], v[152:155], v[192:195], v[36:39]
	v_mfma_f32_16x16x32_bf16 v[48:51], v[144:147], v[200:203], v[48:51]
	v_mfma_f32_16x16x32_bf16 v[32:35], v[152:155], v[200:203], v[32:35]
	v_mfma_f32_16x16x32_bf16 v[28:31], v[156:159], v[172:175], v[28:31]
	v_mfma_f32_16x16x32_bf16 v[12:15], v[164:167], v[172:175], v[12:15]
	v_mfma_f32_16x16x32_bf16 v[24:27], v[156:159], v[180:183], v[24:27]
	v_mfma_f32_16x16x32_bf16 v[8:11], v[164:167], v[180:183], v[8:11]
	v_mfma_f32_16x16x32_bf16 v[20:23], v[156:159], v[188:191], v[20:23]
	v_mfma_f32_16x16x32_bf16 v[4:7], v[164:167], v[188:191], v[4:7]
	v_mfma_f32_16x16x32_bf16 v[16:19], v[156:159], v[196:199], v[16:19]
	v_mfma_f32_16x16x32_bf16 v[0:3], v[164:167], v[196:199], v[0:3]
	v_mfma_f32_16x16x32_bf16 v[28:31], v[160:163], v[176:179], v[28:31]
	v_mfma_f32_16x16x32_bf16 v[12:15], v[168:171], v[176:179], v[12:15]
	v_mfma_f32_16x16x32_bf16 v[24:27], v[160:163], v[184:187], v[24:27]
	v_mfma_f32_16x16x32_bf16 v[8:11], v[168:171], v[184:187], v[8:11]
	v_mfma_f32_16x16x32_bf16 v[20:23], v[160:163], v[192:195], v[20:23]
	v_mfma_f32_16x16x32_bf16 v[4:7], v[168:171], v[192:195], v[4:7]
	v_mfma_f32_16x16x32_bf16 v[16:19], v[160:163], v[200:203], v[16:19]
	v_mfma_f32_16x16x32_bf16 v[0:3], v[168:171], v[200:203], v[0:3]
	s_barrier
	s_add_i32 s74, 0, 0x18000
	s_add_i32 s75, 0, 0x1c000
	v_add_u32_e32 v152, s74, v138
	v_add_u32_e32 v168, s75, v138
	ds_read_b128 v[140:143], v152
	ds_read_b128 v[144:147], v152 offset:1024
	ds_read_b128 v[148:151], v152 offset:2048
	ds_read_b128 v[152:155], v152 offset:3072
	ds_read_b128 v[156:159], v168
	ds_read_b128 v[160:163], v168 offset:1024
	ds_read_b128 v[164:167], v168 offset:2048
	ds_read_b128 v[168:171], v168 offset:3072
	s_add_u32 s30, s40, 0x100000
	s_addc_u32 s31, s41, 0
	s_mov_b32 m0, s59
	v_lshl_add_u64 v[212:213], s[30:31], 0, v[128:129]
	ds_read_b128 v[172:175], v139 offset:32768
	ds_read_b128 v[176:179], v139 offset:33792
	ds_read_b128 v[180:183], v139 offset:34816
	ds_read_b128 v[184:187], v139 offset:35840
	ds_read_b128 v[188:191], v139 offset:36864
	ds_read_b128 v[192:195], v139 offset:37888
	ds_read_b128 v[196:199], v139 offset:38912
	ds_read_b128 v[200:203], v139 offset:39936
	global_load_lds_dwordx4 v[212:213], off
	v_lshl_add_u64 v[212:213], s[30:31], 0, v[130:131]
	s_mov_b32 m0, s60
	s_nop 0
	global_load_lds_dwordx4 v[212:213], off
	s_waitcnt vmcnt(8)
	s_waitcnt lgkmcnt(0)
	s_barrier
	s_waitcnt lgkmcnt(0)
	v_mfma_f32_16x16x32_bf16 v[124:127], v[140:143], v[172:175], v[124:127]
	v_mfma_f32_16x16x32_bf16 v[108:111], v[148:151], v[172:175], v[108:111]
	v_mfma_f32_16x16x32_bf16 v[120:123], v[140:143], v[180:183], v[120:123]
	v_mfma_f32_16x16x32_bf16 v[104:107], v[148:151], v[180:183], v[104:107]
	v_mfma_f32_16x16x32_bf16 v[116:119], v[140:143], v[188:191], v[116:119]
	v_mfma_f32_16x16x32_bf16 v[100:103], v[148:151], v[188:191], v[100:103]
	v_mfma_f32_16x16x32_bf16 v[112:115], v[140:143], v[196:199], v[112:115]
	v_mfma_f32_16x16x32_bf16 v[96:99], v[148:151], v[196:199], v[96:99]
	v_mfma_f32_16x16x32_bf16 v[124:127], v[144:147], v[176:179], v[124:127]
	v_mfma_f32_16x16x32_bf16 v[108:111], v[152:155], v[176:179], v[108:111]
	v_mfma_f32_16x16x32_bf16 v[120:123], v[144:147], v[184:187], v[120:123]
	v_mfma_f32_16x16x32_bf16 v[104:107], v[152:155], v[184:187], v[104:107]
	v_mfma_f32_16x16x32_bf16 v[116:119], v[144:147], v[192:195], v[116:119]
	v_mfma_f32_16x16x32_bf16 v[100:103], v[152:155], v[192:195], v[100:103]
	v_mfma_f32_16x16x32_bf16 v[112:115], v[144:147], v[200:203], v[112:115]
	v_mfma_f32_16x16x32_bf16 v[96:99], v[152:155], v[200:203], v[96:99]
	v_mfma_f32_16x16x32_bf16 v[92:95], v[156:159], v[172:175], v[92:95]
	v_mfma_f32_16x16x32_bf16 v[76:79], v[164:167], v[172:175], v[76:79]
	v_mfma_f32_16x16x32_bf16 v[88:91], v[156:159], v[180:183], v[88:91]
	v_mfma_f32_16x16x32_bf16 v[72:75], v[164:167], v[180:183], v[72:75]
	v_mfma_f32_16x16x32_bf16 v[84:87], v[156:159], v[188:191], v[84:87]
	v_mfma_f32_16x16x32_bf16 v[68:71], v[164:167], v[188:191], v[68:71]
	v_mfma_f32_16x16x32_bf16 v[80:83], v[156:159], v[196:199], v[80:83]
	v_mfma_f32_16x16x32_bf16 v[64:67], v[164:167], v[196:199], v[64:67]
	v_mfma_f32_16x16x32_bf16 v[92:95], v[160:163], v[176:179], v[92:95]
	v_mfma_f32_16x16x32_bf16 v[76:79], v[168:171], v[176:179], v[76:79]
	v_mfma_f32_16x16x32_bf16 v[88:91], v[160:163], v[184:187], v[88:91]
	v_mfma_f32_16x16x32_bf16 v[72:75], v[168:171], v[184:187], v[72:75]
	v_mfma_f32_16x16x32_bf16 v[84:87], v[160:163], v[192:195], v[84:87]
	v_mfma_f32_16x16x32_bf16 v[68:71], v[168:171], v[192:195], v[68:71]
	v_mfma_f32_16x16x32_bf16 v[80:83], v[160:163], v[200:203], v[80:83]
	v_mfma_f32_16x16x32_bf16 v[64:67], v[168:171], v[200:203], v[64:67]
	s_barrier
	s_add_i32 s30, s74, s54
	v_lshl_add_u64 v[204:205], v[204:205], 0, s[6:7]
	s_mov_b32 m0, s30
	ds_read_b128 v[172:175], v139 offset:49152
	ds_read_b128 v[176:179], v139 offset:50176
	ds_read_b128 v[180:183], v139 offset:51200
	ds_read_b128 v[184:187], v139 offset:52224
	ds_read_b128 v[188:191], v139 offset:53248
	ds_read_b128 v[192:195], v139 offset:54272
	ds_read_b128 v[196:199], v139 offset:55296
	ds_read_b128 v[200:203], v139 offset:56320
	global_load_lds_dwordx4 v[204:205], off
	s_add_i32 m0, s30, 0x2000
	s_add_u32 s30, s36, 0x100080
	v_lshl_add_u64 v[204:205], v[206:207], 0, s[6:7]
	s_addc_u32 s31, s37, 0
	s_add_i32 s36, s75, s54
	global_load_lds_dwordx4 v[204:205], off
	v_lshl_add_u64 v[204:205], s[30:31], 0, v[128:129]
	s_mov_b32 m0, s36
	s_nop 0
	global_load_lds_dwordx4 v[204:205], off
	v_lshl_add_u64 v[204:205], s[30:31], 0, v[130:131]
	s_add_i32 m0, s36, 0x2000
	s_nop 0
	global_load_lds_dwordx4 v[204:205], off
	v_lshl_add_u64 v[204:205], v[208:209], 0, s[6:7]
	s_mov_b32 m0, s61
	s_nop 0
	global_load_lds_dwordx4 v[204:205], off
	v_lshl_add_u64 v[204:205], v[210:211], 0, s[6:7]
	s_mov_b32 m0, s62
	s_nop 0
	global_load_lds_dwordx4 v[204:205], off
	s_waitcnt vmcnt(8)
	s_waitcnt lgkmcnt(0)
	s_barrier
	s_waitcnt lgkmcnt(0)
	v_mfma_f32_16x16x32_bf16 v[60:63], v[140:143], v[172:175], v[60:63]
	v_mfma_f32_16x16x32_bf16 v[44:47], v[148:151], v[172:175], v[44:47]
	v_mfma_f32_16x16x32_bf16 v[56:59], v[140:143], v[180:183], v[56:59]
	v_mfma_f32_16x16x32_bf16 v[40:43], v[148:151], v[180:183], v[40:43]
	v_mfma_f32_16x16x32_bf16 v[52:55], v[140:143], v[188:191], v[52:55]
	v_mfma_f32_16x16x32_bf16 v[36:39], v[148:151], v[188:191], v[36:39]
	v_mfma_f32_16x16x32_bf16 v[48:51], v[140:143], v[196:199], v[48:51]
	v_mfma_f32_16x16x32_bf16 v[32:35], v[148:151], v[196:199], v[32:35]
	v_mfma_f32_16x16x32_bf16 v[60:63], v[144:147], v[176:179], v[60:63]
	v_mfma_f32_16x16x32_bf16 v[44:47], v[152:155], v[176:179], v[44:47]
	v_mfma_f32_16x16x32_bf16 v[56:59], v[144:147], v[184:187], v[56:59]
	v_mfma_f32_16x16x32_bf16 v[40:43], v[152:155], v[184:187], v[40:43]
	v_mfma_f32_16x16x32_bf16 v[52:55], v[144:147], v[192:195], v[52:55]
	v_mfma_f32_16x16x32_bf16 v[36:39], v[152:155], v[192:195], v[36:39]
	v_mfma_f32_16x16x32_bf16 v[48:51], v[144:147], v[200:203], v[48:51]
	v_mfma_f32_16x16x32_bf16 v[32:35], v[152:155], v[200:203], v[32:35]
	v_mfma_f32_16x16x32_bf16 v[28:31], v[156:159], v[172:175], v[28:31]
	v_mfma_f32_16x16x32_bf16 v[12:15], v[164:167], v[172:175], v[12:15]
	v_mfma_f32_16x16x32_bf16 v[24:27], v[156:159], v[180:183], v[24:27]
	v_mfma_f32_16x16x32_bf16 v[8:11], v[164:167], v[180:183], v[8:11]
	v_mfma_f32_16x16x32_bf16 v[20:23], v[156:159], v[188:191], v[20:23]
	v_mfma_f32_16x16x32_bf16 v[4:7], v[164:167], v[188:191], v[4:7]
	v_mfma_f32_16x16x32_bf16 v[16:19], v[156:159], v[196:199], v[16:19]
	v_mfma_f32_16x16x32_bf16 v[0:3], v[164:167], v[196:199], v[0:3]
	v_mfma_f32_16x16x32_bf16 v[28:31], v[160:163], v[176:179], v[28:31]
	v_mfma_f32_16x16x32_bf16 v[12:15], v[168:171], v[176:179], v[12:15]
	v_mfma_f32_16x16x32_bf16 v[24:27], v[160:163], v[184:187], v[24:27]
	v_mfma_f32_16x16x32_bf16 v[8:11], v[168:171], v[184:187], v[8:11]
	v_mfma_f32_16x16x32_bf16 v[20:23], v[160:163], v[192:195], v[20:23]
	v_mfma_f32_16x16x32_bf16 v[4:7], v[168:171], v[192:195], v[4:7]
	v_mfma_f32_16x16x32_bf16 v[16:19], v[160:163], v[200:203], v[16:19]
	v_mfma_f32_16x16x32_bf16 v[0:3], v[168:171], v[200:203], v[0:3]
	s_barrier
	s_add_u32 s71, s71, 0x100
	s_addc_u32 s72, s72, 0
	s_cmp_ge_u32 s73, s67
	s_mov_b64 s[30:31], s[34:35]
	s_mov_b32 s36, s73
	s_cbranch_scc0 .LBB0_1859
	s_andn2_b64 vcc, exec, s[48:49]
	s_cbranch_vccnz .LBB0_1851
	v_mov_b32_e32 v0, 0
	s_mov_b32 s64, s22
	s_mov_b32 s63, s24
	s_mov_b64 s[18:19], s[28:29]
	s_mov_b64 s[20:21], s[26:27]
	s_mov_b32 s65, s66
	v_mov_b32_e32 v1, v0
	v_mov_b32_e32 v2, v0
	v_mov_b32_e32 v3, v0
	v_mov_b32_e32 v16, v0
	v_mov_b32_e32 v17, v0
	v_mov_b32_e32 v18, v0
	v_mov_b32_e32 v19, v0
	v_mov_b32_e32 v4, v0
	v_mov_b32_e32 v5, v0
	v_mov_b32_e32 v6, v0
	v_mov_b32_e32 v7, v0
	v_mov_b32_e32 v20, v0
	v_mov_b32_e32 v21, v0
	v_mov_b32_e32 v22, v0
	v_mov_b32_e32 v23, v0
	v_mov_b32_e32 v8, v0
	v_mov_b32_e32 v9, v0
	v_mov_b32_e32 v10, v0
	v_mov_b32_e32 v11, v0
	v_mov_b32_e32 v24, v0
	v_mov_b32_e32 v25, v0
	v_mov_b32_e32 v26, v0
	v_mov_b32_e32 v27, v0
	v_mov_b32_e32 v12, v0
	v_mov_b32_e32 v13, v0
	v_mov_b32_e32 v14, v0
	v_mov_b32_e32 v15, v0
	v_mov_b32_e32 v28, v0
	v_mov_b32_e32 v29, v0
	v_mov_b32_e32 v30, v0
	v_mov_b32_e32 v31, v0
	v_mov_b32_e32 v32, v0
	v_mov_b32_e32 v33, v0
	v_mov_b32_e32 v34, v0
	v_mov_b32_e32 v35, v0
	v_mov_b32_e32 v48, v0
	v_mov_b32_e32 v49, v0
	v_mov_b32_e32 v50, v0
	v_mov_b32_e32 v51, v0
	v_mov_b32_e32 v36, v0
	v_mov_b32_e32 v37, v0
	v_mov_b32_e32 v38, v0
	v_mov_b32_e32 v39, v0
	v_mov_b32_e32 v52, v0
	v_mov_b32_e32 v53, v0
	v_mov_b32_e32 v54, v0
	v_mov_b32_e32 v55, v0
	v_mov_b32_e32 v40, v0
	v_mov_b32_e32 v41, v0
	v_mov_b32_e32 v42, v0
	v_mov_b32_e32 v43, v0
	v_mov_b32_e32 v56, v0
	v_mov_b32_e32 v57, v0
	v_mov_b32_e32 v58, v0
	v_mov_b32_e32 v59, v0
	v_mov_b32_e32 v44, v0
	v_mov_b32_e32 v45, v0
	v_mov_b32_e32 v46, v0
	v_mov_b32_e32 v47, v0
	v_mov_b32_e32 v60, v0
	v_mov_b32_e32 v61, v0
	v_mov_b32_e32 v62, v0
	v_mov_b32_e32 v63, v0
	v_mov_b32_e32 v64, v0
	v_mov_b32_e32 v65, v0
	v_mov_b32_e32 v66, v0
	v_mov_b32_e32 v67, v0
	v_mov_b32_e32 v80, v0
	v_mov_b32_e32 v81, v0
	v_mov_b32_e32 v82, v0
	v_mov_b32_e32 v83, v0
	v_mov_b32_e32 v68, v0
	v_mov_b32_e32 v69, v0
	v_mov_b32_e32 v70, v0
	v_mov_b32_e32 v71, v0
	v_mov_b32_e32 v84, v0
	v_mov_b32_e32 v85, v0
	v_mov_b32_e32 v86, v0
	v_mov_b32_e32 v87, v0
	v_mov_b32_e32 v72, v0
	v_mov_b32_e32 v73, v0
	v_mov_b32_e32 v74, v0
	v_mov_b32_e32 v75, v0
	v_mov_b32_e32 v88, v0
	v_mov_b32_e32 v89, v0
	v_mov_b32_e32 v90, v0
	v_mov_b32_e32 v91, v0
	v_mov_b32_e32 v76, v0
	v_mov_b32_e32 v77, v0
	v_mov_b32_e32 v78, v0
	v_mov_b32_e32 v79, v0
	v_mov_b32_e32 v92, v0
	v_mov_b32_e32 v93, v0
	v_mov_b32_e32 v94, v0
	v_mov_b32_e32 v95, v0
	v_mov_b32_e32 v96, v0
	v_mov_b32_e32 v97, v0
	v_mov_b32_e32 v98, v0
	v_mov_b32_e32 v99, v0
	v_mov_b32_e32 v112, v0
	v_mov_b32_e32 v113, v0
	v_mov_b32_e32 v114, v0
	v_mov_b32_e32 v115, v0
	v_mov_b32_e32 v100, v0
	v_mov_b32_e32 v101, v0
	v_mov_b32_e32 v102, v0
	v_mov_b32_e32 v103, v0
	v_mov_b32_e32 v116, v0
	v_mov_b32_e32 v117, v0
	v_mov_b32_e32 v118, v0
	v_mov_b32_e32 v119, v0
	v_mov_b32_e32 v104, v0
	v_mov_b32_e32 v105, v0
	v_mov_b32_e32 v106, v0
	v_mov_b32_e32 v107, v0
	v_mov_b32_e32 v120, v0
	v_mov_b32_e32 v121, v0
	v_mov_b32_e32 v122, v0
	v_mov_b32_e32 v123, v0
	v_mov_b32_e32 v108, v0
	v_mov_b32_e32 v109, v0
	v_mov_b32_e32 v110, v0
	v_mov_b32_e32 v111, v0
	v_mov_b32_e32 v124, v0
	v_mov_b32_e32 v125, v0
	v_mov_b32_e32 v126, v0
	v_mov_b32_e32 v127, v0
	s_branch .LBB0_1851
